# up/xq GEMM epilogues: LN statistics loads prefetched 2 blocks ahead, fold vectors staged in LDS; sample attention tile cache-row loads batched
# speedup vs baseline: 1.0447x; 1.0110x over previous
; __device__ __forceinline__ unsigned pk2(float lo, float hi) { const f32x2_t v = {lo, hi}; const bf16x2_t b = __builtin_convertvector(v, bf16x2_t); return __builtin_bit_cast(unsigned, b); }
; template <bool SAMPLE> ...
;     ...
;         if (2 * kk + 1 >= kt0) {
; #pragma unroll
;             for (int it = 0; it < 4; ++it) {
;                 const int rl = (lane >> 3) + 8 * it, ch = lane & 7;
;                 u32x4 w;
;                 if (SAMPLE) {
;                     int j = 32 * kk + rl; j = j > 128 ? 128 : j;
;                     const int rr = npre + qi - (j << dsh);
;                     if (rr >= npre) w = *(const u32x4*)(Vb + ((size_t)MP + b * 4 + (rr - npre)) * ATT + h * 64 + ch * 8);
;                     else { const float* vp = cbase + (size_t)rr * 512 + 256 + hs * 64 + ch * 8; const f32x4 a0 = __builtin_nontemporal_load((const f32x4*)vp), a1 = __builtin_nontemporal_load((const f32x4*)(vp + 4));
;                         w.x = pk2(a0.x, a0.y); w.y = pk2(a0.z, a0.w); w.z = pk2(a1.x, a1.y); w.w = pk2(a1.z, a1.w); }
;                 } else {
;                     int sk = s0 - 128 + 32 * kk + rl; sk = sk < 0 ? 0 : sk; sk = sk > s0 + 15 ? s0 + 15 : sk;
;                     w = *(const u32x4*)(Vb + ((size_t)b * SEQ + ((sk << dsh) + r)) * ATT + h * 64 + ch * 8);
;                 }
;                 vr[kk][it] = w;
.LBB0_1593:
	s_or_b64 exec, exec, s[0:1]
	s_lshl_b32 s4, s10, 2
	v_add_u32_e32 v3, s4, v92
	v_lshlrev_b32_e32 v96, s20, v143
	v_sub_u32_e32 v96, s29, v96
	v_lshl_add_u32 v96, v96, 11, v3
	global_load_dwordx4 v[8:11], v96, s[50:51] offset:1024 nt
	global_load_dwordx4 v[96:99], v96, s[50:51] offset:1040 nt
	v_lshlrev_b32_e32 v100, s20, v165
	v_sub_u32_e32 v100, s29, v100
	v_lshl_add_u32 v100, v100, 11, v3
	global_load_dwordx4 v[12:15], v100, s[50:51] offset:1024 nt
	global_load_dwordx4 v[100:103], v100, s[50:51] offset:1040 nt
	v_lshlrev_b32_e32 v104, s20, v166
	v_sub_u32_e32 v104, s29, v104
	v_lshl_add_u32 v104, v104, 11, v3
	global_load_dwordx4 v[24:27], v104, s[50:51] offset:1024 nt
	global_load_dwordx4 v[104:107], v104, s[50:51] offset:1040 nt
	v_lshlrev_b32_e32 v108, s20, v167
	v_sub_u32_e32 v108, s29, v108
	v_lshl_add_u32 v108, v108, 11, v3
	global_load_dwordx4 v[28:31], v108, s[50:51] offset:1024 nt
	global_load_dwordx4 v[108:111], v108, s[50:51] offset:1040 nt
	v_lshlrev_b32_e32 v112, s20, v180
	v_sub_u32_e32 v112, s29, v112
	v_lshl_add_u32 v112, v112, 11, v3
	global_load_dwordx4 v[32:35], v112, s[50:51] offset:1024 nt
	global_load_dwordx4 v[112:115], v112, s[50:51] offset:1040 nt
	v_lshlrev_b32_e32 v116, s20, v181
	v_sub_u32_e32 v116, s29, v116
	v_lshl_add_u32 v116, v116, 11, v3
	global_load_dwordx4 v[36:39], v116, s[50:51] offset:1024 nt
	global_load_dwordx4 v[116:119], v116, s[50:51] offset:1040 nt
	v_lshlrev_b32_e32 v120, s20, v182
	v_sub_u32_e32 v120, s29, v120
	v_lshl_add_u32 v120, v120, 11, v3
	global_load_dwordx4 v[40:43], v120, s[50:51] offset:1024 nt
	global_load_dwordx4 v[120:123], v120, s[50:51] offset:1040 nt
	v_lshlrev_b32_e32 v124, s20, v183
	v_sub_u32_e32 v124, s29, v124
	v_lshl_add_u32 v124, v124, 11, v3
	global_load_dwordx4 v[44:47], v124, s[50:51] offset:1024 nt
	global_load_dwordx4 v[124:127], v124, s[50:51] offset:1040 nt
	v_lshlrev_b32_e32 v128, s20, v184
	v_sub_u32_e32 v128, s29, v128
	v_lshl_add_u32 v128, v128, 11, v3
	global_load_dwordx4 v[48:51], v128, s[50:51] offset:1024 nt
	global_load_dwordx4 v[128:131], v128, s[50:51] offset:1040 nt
	v_lshlrev_b32_e32 v210, s20, v185
	v_sub_u32_e32 v210, s29, v210
	v_lshl_add_u32 v210, v210, 11, v3
	global_load_dwordx4 v[52:55], v210, s[50:51] offset:1024 nt
	global_load_dwordx4 v[210:213], v210, s[50:51] offset:1040 nt
	v_lshlrev_b32_e32 v214, s20, v186
	v_sub_u32_e32 v214, s29, v214
	v_lshl_add_u32 v214, v214, 11, v3
	global_load_dwordx4 v[56:59], v214, s[50:51] offset:1024 nt
	global_load_dwordx4 v[214:217], v214, s[50:51] offset:1040 nt
	v_lshlrev_b32_e32 v234, s20, v187
	v_sub_u32_e32 v234, s29, v234
	v_lshl_add_u32 v234, v234, 11, v3
	global_load_dwordx4 v[60:63], v234, s[50:51] offset:1024 nt
	global_load_dwordx4 v[234:237], v234, s[50:51] offset:1040 nt
	v_lshlrev_b32_e32 v238, s20, v188
	v_sub_u32_e32 v238, s29, v238
	v_lshl_add_u32 v238, v238, 11, v3
	global_load_dwordx4 v[64:67], v238, s[50:51] offset:1024 nt
	global_load_dwordx4 v[238:241], v238, s[50:51] offset:1040 nt
	v_lshlrev_b32_e32 v242, s20, v189
	v_sub_u32_e32 v242, s29, v242
	v_lshl_add_u32 v242, v242, 11, v3
	global_load_dwordx4 v[68:71], v242, s[50:51] offset:1024 nt
	global_load_dwordx4 v[242:245], v242, s[50:51] offset:1040 nt
	v_lshlrev_b32_e32 v246, s20, v190
	v_sub_u32_e32 v246, s29, v246
	v_lshl_add_u32 v246, v246, 11, v3
	global_load_dwordx4 v[72:75], v246, s[50:51] offset:1024 nt
	global_load_dwordx4 v[246:249], v246, s[50:51] offset:1040 nt
	s_waitcnt vmcnt(28)
	v_cvt_pk_bf16_f32 v8, v8, v9
	v_cvt_pk_bf16_f32 v9, v10, v11
	v_cvt_pk_bf16_f32 v10, v96, v97
	v_cvt_pk_bf16_f32 v11, v98, v99
	v_lshlrev_b32_e32 v96, s20, v191
	v_sub_u32_e32 v96, s29, v96
	v_lshl_add_u32 v96, v96, 11, v3
	global_load_dwordx4 v[76:79], v96, s[50:51] offset:1024 nt
	global_load_dwordx4 v[96:99], v96, s[50:51] offset:1040 nt
	s_waitcnt vmcnt(28)
; __device__ __forceinline__ unsigned pk2(float lo, float hi) { const f32x2_t v = {lo, hi}; const bf16x2_t b = __builtin_convertvector(v, bf16x2_t); return __builtin_bit_cast(unsigned, b); }
; template <bool SAMPLE> ...
;     ...
;             for (int it = 0; it < 4; ++it) {
;                 const int rl = (lane >> 3) + 8 * it, ch = lane & 7;
;                 u32x4 w;
;                 if (SAMPLE) {
;                     int j = 32 * kk + rl; j = j > 128 ? 128 : j;
;                     const int rr = npre + qi - (j << dsh);
;                     if (rr >= npre) w = *(const u32x4*)(Vb + ((size_t)MP + b * 4 + (rr - npre)) * ATT + h * 64 + ch * 8);
;                     else { const float* vp = cbase + (size_t)rr * 512 + 256 + hs * 64 + ch * 8; const f32x4 a0 = __builtin_nontemporal_load((const f32x4*)vp), a1 = __builtin_nontemporal_load((const f32x4*)(vp + 4));
;                         w.x = pk2(a0.x, a0.y); w.y = pk2(a0.z, a0.w); w.z = pk2(a1.x, a1.y); w.w = pk2(a1.z, a1.w); }
;                 } else {
;                     int sk = s0 - 128 + 32 * kk + rl; sk = sk < 0 ? 0 : sk; sk = sk > s0 + 15 ? s0 + 15 : sk;
;                     w = *(const u32x4*)(Vb + ((size_t)b * SEQ + ((sk << dsh) + r)) * ATT + h * 64 + ch * 8);
;                 }
;                 vr[kk][it] = w;
;     ...
;             if (SAMPLE) {
;                 int j = 16 * kt + fr; j = j > 128 ? 128 : j;
;                 const int rr = npre + qi - (j << dsh);
;                 if (rr >= npre) { const bf16_t* kp = Kb + ((size_t)MP + b * 4 + (rr - npre)) * ATT + h * 64 + fq * 8; k0 = *(const bf16x8*)kp; k1 = *(const bf16x8*)(kp + 32); }
	v_cvt_pk_bf16_f32 v12, v12, v13
	v_cvt_pk_bf16_f32 v13, v14, v15
	v_cvt_pk_bf16_f32 v14, v100, v101
	v_cvt_pk_bf16_f32 v15, v102, v103
	v_lshlrev_b32_e32 v100, s20, v192
	v_sub_u32_e32 v100, s29, v100
	v_lshl_add_u32 v100, v100, 11, v3
	global_load_dwordx4 v[80:83], v100, s[50:51] offset:1024 nt
	global_load_dwordx4 v[100:103], v100, s[50:51] offset:1040 nt
	s_waitcnt vmcnt(28)
	v_cvt_pk_bf16_f32 v24, v24, v25
	v_cvt_pk_bf16_f32 v25, v26, v27
	v_cvt_pk_bf16_f32 v26, v104, v105
	v_cvt_pk_bf16_f32 v27, v106, v107
	v_lshlrev_b32_e32 v104, s20, v193
	v_sub_u32_e32 v104, s29, v104
	v_lshl_add_u32 v104, v104, 11, v3
	global_load_dwordx4 v[84:87], v104, s[50:51] offset:1024 nt
	global_load_dwordx4 v[104:107], v104, s[50:51] offset:1040 nt
	s_waitcnt vmcnt(28)
	v_cvt_pk_bf16_f32 v28, v28, v29
	v_cvt_pk_bf16_f32 v29, v30, v31
	v_cvt_pk_bf16_f32 v30, v108, v109
	v_cvt_pk_bf16_f32 v31, v110, v111
	v_lshlrev_b32_e32 v108, s20, v194
	v_sub_u32_e32 v108, s29, v108
	v_lshl_add_u32 v108, v108, 11, v3
	global_load_dwordx4 v[88:91], v108, s[50:51] offset:1024 nt
	global_load_dwordx4 v[108:111], v108, s[50:51] offset:1040 nt
	s_waitcnt vmcnt(28)
	v_cvt_pk_bf16_f32 v32, v32, v33
	v_cvt_pk_bf16_f32 v33, v34, v35
	v_cvt_pk_bf16_f32 v34, v112, v113
	v_cvt_pk_bf16_f32 v35, v114, v115
	s_waitcnt vmcnt(26)
	v_cvt_pk_bf16_f32 v36, v36, v37
	v_cvt_pk_bf16_f32 v37, v38, v39
	v_cvt_pk_bf16_f32 v38, v116, v117
	v_cvt_pk_bf16_f32 v39, v118, v119
	s_waitcnt vmcnt(24)
	v_cvt_pk_bf16_f32 v40, v40, v41
	v_cvt_pk_bf16_f32 v41, v42, v43
	v_cvt_pk_bf16_f32 v42, v120, v121
	v_cvt_pk_bf16_f32 v43, v122, v123
	s_waitcnt vmcnt(22)
	v_cvt_pk_bf16_f32 v44, v44, v45
	v_cvt_pk_bf16_f32 v45, v46, v47
	v_cvt_pk_bf16_f32 v46, v124, v125
	v_cvt_pk_bf16_f32 v47, v126, v127
	s_waitcnt vmcnt(20)
	v_cvt_pk_bf16_f32 v48, v48, v49
	v_cvt_pk_bf16_f32 v49, v50, v51
	v_cvt_pk_bf16_f32 v50, v128, v129
	v_cvt_pk_bf16_f32 v51, v130, v131
	s_waitcnt vmcnt(18)
	v_cvt_pk_bf16_f32 v52, v52, v53
	v_cvt_pk_bf16_f32 v53, v54, v55
	v_cvt_pk_bf16_f32 v54, v210, v211
	v_cvt_pk_bf16_f32 v55, v212, v213
	s_waitcnt vmcnt(16)
	v_cvt_pk_bf16_f32 v56, v56, v57
	v_cvt_pk_bf16_f32 v57, v58, v59
	v_cvt_pk_bf16_f32 v58, v214, v215
	v_cvt_pk_bf16_f32 v59, v216, v217
	s_waitcnt vmcnt(14)
	v_cvt_pk_bf16_f32 v60, v60, v61
	v_cvt_pk_bf16_f32 v61, v62, v63
	v_cvt_pk_bf16_f32 v62, v234, v235
	v_cvt_pk_bf16_f32 v63, v236, v237
	s_waitcnt vmcnt(12)
	v_cvt_pk_bf16_f32 v64, v64, v65
	v_cvt_pk_bf16_f32 v65, v66, v67
	v_cvt_pk_bf16_f32 v66, v238, v239
	v_cvt_pk_bf16_f32 v67, v240, v241
	s_waitcnt vmcnt(10)
	v_cvt_pk_bf16_f32 v68, v68, v69
	v_cvt_pk_bf16_f32 v69, v70, v71
	v_cvt_pk_bf16_f32 v70, v242, v243
	v_cvt_pk_bf16_f32 v71, v244, v245
	s_waitcnt vmcnt(8)
	v_cvt_pk_bf16_f32 v72, v72, v73
	v_cvt_pk_bf16_f32 v73, v74, v75
	v_cvt_pk_bf16_f32 v74, v246, v247
	v_cvt_pk_bf16_f32 v75, v248, v249
	s_waitcnt vmcnt(6)
	v_cvt_pk_bf16_f32 v76, v76, v77
	v_cvt_pk_bf16_f32 v77, v78, v79
	v_cvt_pk_bf16_f32 v78, v96, v97
	v_cvt_pk_bf16_f32 v79, v98, v99
	s_waitcnt vmcnt(4)
	v_cvt_pk_bf16_f32 v80, v80, v81
	v_cvt_pk_bf16_f32 v81, v82, v83
	v_cvt_pk_bf16_f32 v82, v100, v101
	v_cvt_pk_bf16_f32 v83, v102, v103
	s_waitcnt vmcnt(2)
	v_cvt_pk_bf16_f32 v84, v84, v85
	v_cvt_pk_bf16_f32 v85, v86, v87
	v_cvt_pk_bf16_f32 v86, v104, v105
	v_cvt_pk_bf16_f32 v87, v106, v107
	s_waitcnt vmcnt(0)
	v_cvt_pk_bf16_f32 v88, v88, v89
	v_cvt_pk_bf16_f32 v89, v90, v91
	v_cvt_pk_bf16_f32 v90, v108, v109
	v_cvt_pk_bf16_f32 v91, v110, v111
	s_lshl_b32 s4, s11, 1
	s_lshl_b32 s0, s10, 2
	v_lshlrev_b32_e32 v3, s20, v160
	s_add_u32 s0, s50, s0
	v_sub_u32_e32 v100, s29, v3
	v_lshl_add_u64 v[0:1], v[148:149], 0, s[4:5]
	s_addc_u32 s1, s51, 0
	v_cmp_le_i32_e32 vcc, s23, v100
	s_and_saveexec_b64 s[10:11], vcc
	s_xor_b64 s[10:11], exec, s[10:11]
	s_cbranch_execz .LBB0_1671
	v_subrev_u32_e32 v92, s23, v100
	v_mov_b32_e32 v93, v2
	v_lshl_add_u64 v[92:93], s[6:7], 0, v[92:93]
	v_mad_u64_u32 v[96:97], s[50:51], v92, s28, v[0:1]
	v_mad_i32_i24 v97, v93, s28, v97
	global_load_dwordx4 v[92:95], v[96:97], off
	s_nop 0
	global_load_dwordx4 v[96:99], v[96:97], off offset:64

; __device__ __forceinline__ unsigned pk2(float lo, float hi) { const f32x2_t v = {lo, hi}; const bf16x2_t b = __builtin_convertvector(v, bf16x2_t); return __builtin_bit_cast(unsigned, b); }
; template <bool SAMPLE> ...
;     ...
;         if (kt >= kt0) {
;             bf16x8 k0, k1;
;             if (SAMPLE) {
;                 int j = 16 * kt + fr; j = j > 128 ? 128 : j;
;                 const int rr = npre + qi - (j << dsh);
;                 if (rr >= npre) { const bf16_t* kp = Kb + ((size_t)MP + b * 4 + (rr - npre)) * ATT + h * 64 + fq * 8; k0 = *(const bf16x8*)kp; k1 = *(const bf16x8*)(kp + 32); }
;                 else { const float* kp = cbase + (size_t)rr * 512 + hs * 64 + fq * 8;
;                     const f32x4 a0 = __builtin_nontemporal_load((const f32x4*)kp), a1 = __builtin_nontemporal_load((const f32x4*)(kp + 4)), a2 = __builtin_nontemporal_load((const f32x4*)(kp + 32)), a3 = __builtin_nontemporal_load((const f32x4*)(kp + 36));
;                     u32x4 w0, w1; w0.x = pk2(a0.x, a0.y); w0.y = pk2(a0.z, a0.w); w0.z = pk2(a1.x, a1.y); w0.w = pk2(a1.z, a1.w);
;                     w1.x = pk2(a2.x, a2.y); w1.y = pk2(a2.z, a2.w); w1.z = pk2(a3.x, a3.y); w1.w = pk2(a3.z, a3.w);
;                     k0 = __builtin_bit_cast(bf16x8, w0); k1 = __builtin_bit_cast(bf16x8, w1); }
;             } else {
;                 const int sk = s0 - 128 + 16 * kt + fr;
;                 const bf16_t* kp = Kb + ((size_t)b * SEQ + ((sk << dsh) + r)) * ATT + h * 64 + fq * 8;
;                 k0 = *(const bf16x8*)kp; k1 = *(const bf16x8*)(kp + 32);
;             }
;             f32x4 a = (f32x4){0.f, 0.f, 0.f, 0.f};
;             a = __builtin_amdgcn_mfma_f32_16x16x32_bf16(k0, q0, a, 0, 0, 0);
;             a = __builtin_amdgcn_mfma_f32_16x16x32_bf16(k1, q1, a, 0, 0, 0);
;             S[kt] = a;
.LBB0_1673:
	s_or_b64 exec, exec, s[50:51]
	v_lshlrev_b32_e32 v214, s20, v195
	v_sub_u32_e32 v214, s29, v214
	v_lshlrev_b32_e32 v214, 11, v214
	v_mov_b32_e32 v215, 0
	v_lshl_add_u64 v[214:215], v[214:215], 0, v[158:159]
	global_load_dwordx4 v[124:127], v[214:215], off nt
	global_load_dwordx4 v[128:131], v[214:215], off offset:16 nt
	global_load_dwordx4 v[210:213], v[214:215], off offset:128 nt
	global_load_dwordx4 v[214:217], v[214:215], off offset:144 nt
	v_lshlrev_b32_e32 v246, s20, v196
	v_sub_u32_e32 v246, s29, v246
	v_lshlrev_b32_e32 v246, 11, v246
	v_mov_b32_e32 v247, 0
	v_lshl_add_u64 v[246:247], v[246:247], 0, v[158:159]
	global_load_dwordx4 v[234:237], v[246:247], off nt
	global_load_dwordx4 v[238:241], v[246:247], off offset:16 nt
	global_load_dwordx4 v[242:245], v[246:247], off offset:128 nt
	global_load_dwordx4 v[246:249], v[246:247], off offset:144 nt
	s_waitcnt vmcnt(9)
	v_mfma_f32_16x16x32_bf16 v[92:95], v[92:95], v[20:23], 0
	s_waitcnt vmcnt(8)
	v_mfma_f32_16x16x32_bf16 v[92:95], v[96:99], v[16:19], v[92:95]
	s_waitcnt vmcnt(4)
	v_cvt_pk_bf16_f32 v124, v124, v125
	v_cvt_pk_bf16_f32 v125, v126, v127
	v_cvt_pk_bf16_f32 v126, v128, v129
	v_cvt_pk_bf16_f32 v127, v130, v131
	v_cvt_pk_bf16_f32 v210, v210, v211
	v_cvt_pk_bf16_f32 v211, v212, v213
	v_cvt_pk_bf16_f32 v212, v214, v215
	v_cvt_pk_bf16_f32 v213, v216, v217
	s_nop 1
	v_mfma_f32_16x16x32_bf16 v[96:99], v[124:127], v[20:23], 0
	v_mfma_f32_16x16x32_bf16 v[96:99], v[210:213], v[16:19], v[96:99]
	v_lshlrev_b32_e32 v214, s20, v197
	v_sub_u32_e32 v214, s29, v214
	v_lshlrev_b32_e32 v214, 11, v214
	v_mov_b32_e32 v215, 0
	v_lshl_add_u64 v[214:215], v[214:215], 0, v[158:159]
	global_load_dwordx4 v[124:127], v[214:215], off nt
	global_load_dwordx4 v[128:131], v[214:215], off offset:16 nt
	global_load_dwordx4 v[210:213], v[214:215], off offset:128 nt
	global_load_dwordx4 v[214:217], v[214:215], off offset:144 nt
	s_waitcnt vmcnt(4)
	v_cvt_pk_bf16_f32 v234, v234, v235
	v_cvt_pk_bf16_f32 v235, v236, v237
	v_cvt_pk_bf16_f32 v236, v238, v239
	v_cvt_pk_bf16_f32 v237, v240, v241
	v_cvt_pk_bf16_f32 v242, v242, v243
	v_cvt_pk_bf16_f32 v243, v244, v245
	v_cvt_pk_bf16_f32 v244, v246, v247
	v_cvt_pk_bf16_f32 v245, v248, v249
	s_nop 1
	v_mfma_f32_16x16x32_bf16 v[100:103], v[234:237], v[20:23], 0
	v_mfma_f32_16x16x32_bf16 v[100:103], v[242:245], v[16:19], v[100:103]
	v_lshlrev_b32_e32 v246, s20, v198
	v_sub_u32_e32 v246, s29, v246
	v_lshlrev_b32_e32 v246, 11, v246
	v_mov_b32_e32 v247, 0
	v_lshl_add_u64 v[246:247], v[246:247], 0, v[158:159]
	global_load_dwordx4 v[234:237], v[246:247], off nt
	global_load_dwordx4 v[238:241], v[246:247], off offset:16 nt
	global_load_dwordx4 v[242:245], v[246:247], off offset:128 nt
	global_load_dwordx4 v[246:249], v[246:247], off offset:144 nt
	s_waitcnt vmcnt(4)
	v_cvt_pk_bf16_f32 v124, v124, v125
	v_cvt_pk_bf16_f32 v125, v126, v127
	v_cvt_pk_bf16_f32 v126, v128, v129
	v_cvt_pk_bf16_f32 v127, v130, v131
	v_cvt_pk_bf16_f32 v210, v210, v211
	v_cvt_pk_bf16_f32 v211, v212, v213
	v_cvt_pk_bf16_f32 v212, v214, v215
	v_cvt_pk_bf16_f32 v213, v216, v217
	s_nop 1
	v_mfma_f32_16x16x32_bf16 v[104:107], v[124:127], v[20:23], 0
	v_mfma_f32_16x16x32_bf16 v[104:107], v[210:213], v[16:19], v[104:107]
	v_lshlrev_b32_e32 v214, s20, v199
	v_sub_u32_e32 v214, s29, v214
	v_lshlrev_b32_e32 v214, 11, v214
	v_mov_b32_e32 v215, 0
	v_lshl_add_u64 v[214:215], v[214:215], 0, v[158:159]
	global_load_dwordx4 v[124:127], v[214:215], off nt
	global_load_dwordx4 v[128:131], v[214:215], off offset:16 nt
	global_load_dwordx4 v[210:213], v[214:215], off offset:128 nt
	global_load_dwordx4 v[214:217], v[214:215], off offset:144 nt
	s_waitcnt vmcnt(4)
	v_cvt_pk_bf16_f32 v234, v234, v235
	v_cvt_pk_bf16_f32 v235, v236, v237
	v_cvt_pk_bf16_f32 v236, v238, v239
	v_cvt_pk_bf16_f32 v237, v240, v241
	v_cvt_pk_bf16_f32 v242, v242, v243
	v_cvt_pk_bf16_f32 v243, v244, v245
	v_cvt_pk_bf16_f32 v244, v246, v247
	v_cvt_pk_bf16_f32 v245, v248, v249
	s_nop 1
	v_mfma_f32_16x16x32_bf16 v[108:111], v[234:237], v[20:23], 0
	v_mfma_f32_16x16x32_bf16 v[108:111], v[242:245], v[16:19], v[108:111]
	v_lshlrev_b32_e32 v246, s20, v200
	v_sub_u32_e32 v246, s29, v246
	v_lshlrev_b32_e32 v246, 11, v246
	v_mov_b32_e32 v247, 0
	v_lshl_add_u64 v[246:247], v[246:247], 0, v[158:159]
	global_load_dwordx4 v[234:237], v[246:247], off nt
	global_load_dwordx4 v[238:241], v[246:247], off offset:16 nt
	global_load_dwordx4 v[242:245], v[246:247], off offset:128 nt
	global_load_dwordx4 v[246:249], v[246:247], off offset:144 nt
	s_waitcnt vmcnt(4)
	v_cvt_pk_bf16_f32 v124, v124, v125
	v_cvt_pk_bf16_f32 v125, v126, v127
	v_cvt_pk_bf16_f32 v126, v128, v129
	v_cvt_pk_bf16_f32 v127, v130, v131
	v_cvt_pk_bf16_f32 v210, v210, v211
	v_cvt_pk_bf16_f32 v211, v212, v213
	v_cvt_pk_bf16_f32 v212, v214, v215
	v_cvt_pk_bf16_f32 v213, v216, v217
	s_nop 1
	v_mfma_f32_16x16x32_bf16 v[120:123], v[124:127], v[20:23], 0
	v_mfma_f32_16x16x32_bf16 v[120:123], v[210:213], v[16:19], v[120:123]
	v_lshlrev_b32_e32 v214, s20, v201
	v_sub_u32_e32 v214, s29, v214
	v_lshlrev_b32_e32 v214, 11, v214
	v_mov_b32_e32 v215, 0
	v_lshl_add_u64 v[214:215], v[214:215], 0, v[158:159]
	global_load_dwordx4 v[124:127], v[214:215], off nt
	global_load_dwordx4 v[128:131], v[214:215], off offset:16 nt
	global_load_dwordx4 v[210:213], v[214:215], off offset:128 nt
	global_load_dwordx4 v[214:217], v[214:215], off offset:144 nt
	s_waitcnt vmcnt(4)
	v_cvt_pk_bf16_f32 v234, v234, v235
	v_cvt_pk_bf16_f32 v235, v236, v237
	v_cvt_pk_bf16_f32 v236, v238, v239
	v_cvt_pk_bf16_f32 v237, v240, v241
	v_cvt_pk_bf16_f32 v242, v242, v243
	v_cvt_pk_bf16_f32 v243, v244, v245
	v_cvt_pk_bf16_f32 v244, v246, v247
	v_cvt_pk_bf16_f32 v245, v248, v249
	s_nop 1
	v_mfma_f32_16x16x32_bf16 v[112:115], v[234:237], v[20:23], 0
	v_mfma_f32_16x16x32_bf16 v[112:115], v[242:245], v[16:19], v[112:115]
	s_waitcnt vmcnt(0)
	v_cvt_pk_bf16_f32 v124, v124, v125
	v_cvt_pk_bf16_f32 v125, v126, v127
	v_cvt_pk_bf16_f32 v126, v128, v129
	v_cvt_pk_bf16_f32 v127, v130, v131
	v_cvt_pk_bf16_f32 v210, v210, v211
	v_cvt_pk_bf16_f32 v211, v212, v213
	v_cvt_pk_bf16_f32 v212, v214, v215
	v_cvt_pk_bf16_f32 v213, v216, v217
	s_nop 1
	v_mfma_f32_16x16x32_bf16 v[116:119], v[124:127], v[20:23], 0
	v_mfma_f32_16x16x32_bf16 v[116:119], v[210:213], v[16:19], v[116:119]
	s_lshl_b32 s0, 0xffffff80, s20
	s_add_i32 s0, s29, s0
	s_mov_b64 s[10:11], -1
	s_cmp_lt_i32 s0, s23
	s_cbranch_scc1 .LBB0_1703
	s_sub_i32 s1, s0, s23
	s_add_u32 s1, s6, s1
	s_addc_u32 s4, s7, 0
	s_mulk_i32 s4, 0x600
	v_mad_u64_u32 v[0:1], s[10:11], s1, v231, v[0:1]
	v_add_u32_e32 v1, s4, v1
	global_load_dwordx4 v[128:131], v[0:1], off
	global_load_dwordx4 v[124:127], v[0:1], off offset:64
	s_mov_b64 s[10:11], 0

;     __device__ __forceinline__ void operator()(int row, int col, f32x4 v, int, float&, float&) const { *(u32x2*)(O + (size_t)row * ldc + col) = pk4(v * s); }
; __device__ __forceinline__ void stats_main(const float* stm, int row, int fq, float& mu, float& rs) {
;     const f32x4* p = (const f32x4*)(stm + (size_t)row * 32 + fq * 8);
;     const f32x4 a = p[0], b = p[1];
;     float s1 = (a.x + a.z) + (b.x + b.z), s2 = (a.y + a.w) + (b.y + b.w);
;     s1 += __shfl_xor(s1, 16); s2 += __shfl_xor(s2, 16); s1 += __shfl_xor(s1, 32); s2 += __shfl_xor(s2, 32);
;     mu = s1 * (1.f / DM); rs = __builtin_amdgcn_rsqf(fmaxf(s2 * (1.f / DM) - mu * mu, 0.f) + LN_EPS);
; }
;     __device__ __forceinline__ void operator()(const f32x4 (&acc)[2][2][4][2], const pg8::Unit& u, int wr, int wc, int fr, int fq) const {
;         float mu[2][4], rs[2][4], ps1[2][4], ps2[2][4];
; #pragma unroll
;         for (int ai = 0; ai < 2; ++ai)
; #pragma unroll
;             for (int m = 0; m < 4; ++m) { ps1[ai][m] = 0.f; ps2[ai][m] = 0.f; mu[ai][m] = 0.f; rs[ai][m] = 1.f; if (fold) stats_main(stm, u.pm * 256 + ai * 128 + wr * 64 + m * 16 + fr, fq, mu[ai][m], rs[ai][m]); }
; #pragma unroll
;         for (int bj = 0; bj < 2; ++bj)
; #pragma unroll
;             for (int n = 0; n < 2; ++n) {
;                 const int col = u.pn * 256 + bj * 128 + wc * 32 + n * 16 + fq * 4;
;                 f32x4 c1v = (f32x4){0.f, 0.f, 0.f, 0.f}, c2v = c1v;
;                 if (fold) { c1v = *(const f32x4*)(c1 + col); c2v = *(const f32x4*)(c2 + col); }
.LBB0_2026:
	v_and_b32_e32 v238, 0xfffffff0, v155
	v_lshl_add_u32 v238, s22, 8, v238
	v_and_b32_e32 v239, 31, v219
	v_add_u32_e32 v238, v238, v239
	v_lshrrev_b32_e32 v239, 5, v219
	v_lshl_add_u32 v238, v239, 7, v238
	v_lshlrev_b32_e32 v238, 2, v238
	global_load_dword v242, v238, s[42:43]
	global_load_dword v243, v238, s[46:47]
	v_lshl_add_u32 v238, s23, 8, v3
	v_lshlrev_b32_e32 v246, 7, v238
	v_mov_b32_e32 v247, 0
	v_lshlrev_b32_e32 v248, 7, v238
	v_mov_b32_e32 v249, 0
	v_add_u32_e32 v246, 0x1000, v246
	v_add_u32_e32 v248, 0x5000, v248
	v_lshl_add_u64 v[246:247], v[246:247], 0, v[142:143]
	v_lshl_add_u64 v[248:249], v[248:249], 0, v[142:143]
	global_load_dwordx4 v[214:217], v[246:247], off offset:-4080
	global_load_dwordx4 v[234:237], v[246:247], off offset:-4096
	v_lshrrev_b32_e32 v238, 6, v3
	v_lshrrev_b32_e32 v239, 5, v155
	v_lshl_add_u32 v238, v238, 2, v239
	v_lshlrev_b32_e32 v238, 9, v238
	v_and_b32_e32 v239, 12, v155
	v_lshl_add_u32 v255, v239, 2, v238
	v_add_u32_e32 v255, 0x20000, v255
	v_lshl_add_u32 v238, v219, 2, v238
	v_add_u32_e32 v238, 0x20000, v238
	s_waitcnt vmcnt(3)
	ds_write_b32 v238, v242
	s_waitcnt vmcnt(2)
	ds_write_b32 v238, v243 offset:256
	global_load_dwordx4 v[238:241], v[246:247], off offset:-2032
	global_load_dwordx4 v[242:245], v[246:247], off offset:-2048
	s_waitcnt lgkmcnt(0)
	v_lshl_add_u32 v192, s23, 8, v3
	v_ashrrev_i32_e32 v193, 31, v192
	v_lshlrev_b64 v[132:133], 7, v[192:193]
	v_lshl_add_u64 v[136:137], v[142:143], 0, v[132:133]
	s_waitcnt vmcnt(3)
	v_mov_b64_e32 v[132:133], v[214:215]
	v_mov_b64_e32 v[134:135], v[216:217]
	global_load_dwordx4 v[214:217], v[246:247], off offset:16
	s_nop 0
	s_waitcnt vmcnt(3)
	v_mov_b64_e32 v[136:137], v[234:235]
	v_mov_b64_e32 v[138:139], v[236:237]
	global_load_dwordx4 v[234:237], v[246:247], off
	v_and_b32_e32 v149, 64, v219
	v_xor_b32_e32 v148, 16, v219
	v_add_u32_e32 v149, 64, v149
	v_cmp_lt_i32_e32 vcc, v148, v149
	v_or_b32_e32 v194, 16, v192
	v_ashrrev_i32_e32 v195, 31, v194
	v_cndmask_b32_e32 v148, v219, v148, vcc
	v_lshlrev_b32_e32 v163, 2, v148
	v_xor_b32_e32 v148, 32, v219
	v_cmp_lt_i32_e32 vcc, v148, v149
	v_or_b32_e32 v196, 32, v192
	v_ashrrev_i32_e32 v197, 31, v196
	v_cndmask_b32_e32 v148, v219, v148, vcc
	v_lshlrev_b32_e32 v167, 2, v148
	v_or_b32_e32 v198, 48, v192
	v_ashrrev_i32_e32 v199, 31, v198
	v_add_u32_e32 v200, 0x80, v192
	v_ashrrev_i32_e32 v201, 31, v200
	v_add_u32_e32 v202, 0x90, v192
	v_ashrrev_i32_e32 v203, 31, v202
	v_add_u32_e32 v206, 0xa0, v192
	v_ashrrev_i32_e32 v207, 31, v206
	v_add_u32_e32 v204, 0xb0, v192
	v_ashrrev_i32_e32 v205, 31, v204
	v_lshl_add_u32 v208, s22, 8, v155
	v_ashrrev_i32_e32 v209, 31, v208
	v_readlane_b32 s0, v252, 19
	v_readlane_b32 s1, v252, 20
	v_readlane_b32 s24, v251, 0
	s_andn2_b64 vcc, exec, s[40:41]
	v_readlane_b32 s25, v251, 1
	v_readlane_b32 s26, v251, 2
	v_readlane_b32 s27, v251, 3
	s_waitcnt lgkmcnt(0)
	v_pk_add_f32 v[132:133], v[132:133], v[134:135]
	v_pk_add_f32 v[136:137], v[136:137], v[138:139]
	s_nop 0
	v_pk_add_f32 v[132:133], v[136:137], v[132:133]
	ds_bpermute_b32 v134, v163, v132
	ds_bpermute_b32 v135, v163, v133
	s_waitcnt lgkmcnt(0)
	v_pk_add_f32 v[132:133], v[132:133], v[134:135]
	ds_bpermute_b32 v134, v167, v132
	ds_bpermute_b32 v135, v167, v133
	s_waitcnt lgkmcnt(0)
	v_pk_add_f32 v[132:133], v[132:133], v[134:135]
	s_nop 0
	v_pk_mul_f32 v[148:149], v[132:133], s[82:83] op_sel_hi:[1,0]
	s_nop 0
	v_fma_f32 v132, -v148, v148, v149
	v_max_f32_e32 v132, 0, v132
	v_add_f32_e32 v132, 0x3727c5ac, v132
	v_rsq_f32_e32 v150, v132
	v_lshlrev_b64 v[132:133], 7, v[194:195]
	v_lshl_add_u64 v[136:137], v[142:143], 0, v[132:133]
	s_waitcnt vmcnt(3)
	v_mov_b64_e32 v[132:133], v[238:239]
	v_mov_b64_e32 v[134:135], v[240:241]
	global_load_dwordx4 v[238:241], v[246:247], off offset:2064
	s_nop 0
	s_waitcnt vmcnt(3)
	v_mov_b64_e32 v[136:137], v[242:243]
	v_mov_b64_e32 v[138:139], v[244:245]
	global_load_dwordx4 v[242:245], v[246:247], off offset:2048
	s_waitcnt lgkmcnt(0)
	v_pk_add_f32 v[132:133], v[132:133], v[134:135]
	s_waitcnt lgkmcnt(0)
	v_pk_add_f32 v[136:137], v[136:137], v[138:139]
	s_nop 0
	v_pk_add_f32 v[132:133], v[136:137], v[132:133]
	ds_bpermute_b32 v134, v163, v132
	ds_bpermute_b32 v135, v163, v133
	s_waitcnt lgkmcnt(0)
	v_pk_add_f32 v[132:133], v[132:133], v[134:135]
	ds_bpermute_b32 v134, v167, v132
	ds_bpermute_b32 v135, v167, v133
	s_waitcnt lgkmcnt(0)
	v_pk_add_f32 v[132:133], v[132:133], v[134:135]
	s_nop 0
	v_pk_mul_f32 v[152:153], v[132:133], s[82:83] op_sel_hi:[1,0]
	s_nop 0
	v_fma_f32 v132, -v152, v152, v153
	v_max_f32_e32 v132, 0, v132
	v_add_f32_e32 v132, 0x3727c5ac, v132
	v_rsq_f32_e32 v154, v132
	v_lshlrev_b64 v[132:133], 7, v[196:197]
	v_lshl_add_u64 v[136:137], v[142:143], 0, v[132:133]
	s_waitcnt vmcnt(3)
	v_mov_b64_e32 v[132:133], v[214:215]
	v_mov_b64_e32 v[134:135], v[216:217]
	global_load_dwordx4 v[214:217], v[248:249], off offset:-4080
	s_nop 0
	s_waitcnt vmcnt(3)
	v_mov_b64_e32 v[136:137], v[234:235]
	v_mov_b64_e32 v[138:139], v[236:237]
	global_load_dwordx4 v[234:237], v[248:249], off offset:-4096
	s_waitcnt lgkmcnt(0)
	v_pk_add_f32 v[132:133], v[132:133], v[134:135]
	s_waitcnt lgkmcnt(0)
	v_pk_add_f32 v[136:137], v[136:137], v[138:139]
	s_nop 0
	v_pk_add_f32 v[132:133], v[136:137], v[132:133]
	ds_bpermute_b32 v134, v163, v132
	ds_bpermute_b32 v135, v163, v133
	s_waitcnt lgkmcnt(0)
	v_pk_add_f32 v[132:133], v[132:133], v[134:135]
	ds_bpermute_b32 v134, v167, v132
	ds_bpermute_b32 v135, v167, v133
	s_waitcnt lgkmcnt(0)
; __device__ __forceinline__ void stats_main(const float* stm, int row, int fq, float& mu, float& rs) {
;     const f32x4* p = (const f32x4*)(stm + (size_t)row * 32 + fq * 8);
;     const f32x4 a = p[0], b = p[1];
;     float s1 = (a.x + a.z) + (b.x + b.z), s2 = (a.y + a.w) + (b.y + b.w);
;     s1 += __shfl_xor(s1, 16); s2 += __shfl_xor(s2, 16); s1 += __shfl_xor(s1, 32); s2 += __shfl_xor(s2, 32);
;     mu = s1 * (1.f / DM); rs = __builtin_amdgcn_rsqf(fmaxf(s2 * (1.f / DM) - mu * mu, 0.f) + LN_EPS);
; }
;     __device__ __forceinline__ void operator()(const f32x4 (&acc)[2][2][4][2], const pg8::Unit& u, int wr, int wc, int fr, int fq) const {
;     ...
;             for (int m = 0; m < 4; ++m) { ps1[ai][m] = 0.f; ps2[ai][m] = 0.f; mu[ai][m] = 0.f; rs[ai][m] = 1.f; if (fold) stats_main(stm, u.pm * 256 + ai * 128 + wr * 64 + m * 16 + fr, fq, mu[ai][m], rs[ai][m]); }
; #pragma unroll
;         for (int bj = 0; bj < 2; ++bj)
; #pragma unroll
;             for (int n = 0; n < 2; ++n) {
;                 const int col = u.pn * 256 + bj * 128 + wc * 32 + n * 16 + fq * 4;
;                 f32x4 c1v = (f32x4){0.f, 0.f, 0.f, 0.f}, c2v = c1v;
;                 if (fold) { c1v = *(const f32x4*)(c1 + col); c2v = *(const f32x4*)(c2 + col); }
	v_pk_add_f32 v[132:133], v[132:133], v[134:135]
	s_nop 0
	v_pk_mul_f32 v[156:157], v[132:133], s[82:83] op_sel_hi:[1,0]
	s_nop 0
	v_fma_f32 v132, -v156, v156, v157
	v_max_f32_e32 v132, 0, v132
	v_add_f32_e32 v132, 0x3727c5ac, v132
	v_rsq_f32_e32 v158, v132
	v_lshlrev_b64 v[132:133], 7, v[198:199]
	v_lshl_add_u64 v[136:137], v[142:143], 0, v[132:133]
	s_waitcnt vmcnt(3)
	v_mov_b64_e32 v[132:133], v[238:239]
	v_mov_b64_e32 v[134:135], v[240:241]
	global_load_dwordx4 v[238:241], v[248:249], off offset:-2032
	s_nop 0
	s_waitcnt vmcnt(3)
	v_mov_b64_e32 v[136:137], v[242:243]
	v_mov_b64_e32 v[138:139], v[244:245]
	global_load_dwordx4 v[242:245], v[248:249], off offset:-2048
	s_waitcnt lgkmcnt(0)
	v_pk_add_f32 v[132:133], v[132:133], v[134:135]
	s_waitcnt lgkmcnt(0)
	v_pk_add_f32 v[136:137], v[136:137], v[138:139]
	s_nop 0
	v_pk_add_f32 v[132:133], v[136:137], v[132:133]
	ds_bpermute_b32 v134, v163, v132
	ds_bpermute_b32 v135, v163, v133
	s_waitcnt lgkmcnt(0)
	v_pk_add_f32 v[132:133], v[132:133], v[134:135]
	ds_bpermute_b32 v134, v167, v132
	ds_bpermute_b32 v135, v167, v133
	s_waitcnt lgkmcnt(0)
	v_pk_add_f32 v[132:133], v[132:133], v[134:135]
	s_nop 0
	v_pk_mul_f32 v[160:161], v[132:133], s[82:83] op_sel_hi:[1,0]
	s_nop 0
	v_fma_f32 v132, -v160, v160, v161
	v_max_f32_e32 v132, 0, v132
	v_add_f32_e32 v132, 0x3727c5ac, v132
	v_rsq_f32_e32 v162, v132
	v_lshlrev_b64 v[132:133], 7, v[200:201]
	v_lshl_add_u64 v[136:137], v[142:143], 0, v[132:133]
	s_waitcnt vmcnt(3)
	v_mov_b64_e32 v[132:133], v[214:215]
	v_mov_b64_e32 v[134:135], v[216:217]
	global_load_dwordx4 v[214:217], v[248:249], off offset:16
	s_nop 0
	s_waitcnt vmcnt(3)
	v_mov_b64_e32 v[136:137], v[234:235]
	v_mov_b64_e32 v[138:139], v[236:237]
	global_load_dwordx4 v[234:237], v[248:249], off
	s_waitcnt lgkmcnt(0)
	v_pk_add_f32 v[132:133], v[132:133], v[134:135]
	s_waitcnt lgkmcnt(0)
	v_pk_add_f32 v[136:137], v[136:137], v[138:139]
	s_nop 0
	v_pk_add_f32 v[132:133], v[136:137], v[132:133]
	ds_bpermute_b32 v134, v163, v132
	ds_bpermute_b32 v135, v163, v133
	s_waitcnt lgkmcnt(0)
	v_pk_add_f32 v[132:133], v[132:133], v[134:135]
	ds_bpermute_b32 v134, v167, v132
	ds_bpermute_b32 v135, v167, v133
	s_waitcnt lgkmcnt(0)
	v_pk_add_f32 v[132:133], v[132:133], v[134:135]
	s_nop 0
	v_pk_mul_f32 v[164:165], v[132:133], s[82:83] op_sel_hi:[1,0]
	s_nop 0
	v_fma_f32 v132, -v164, v164, v165
	v_max_f32_e32 v132, 0, v132
	v_add_f32_e32 v132, 0x3727c5ac, v132
	v_rsq_f32_e32 v166, v132
	v_lshlrev_b64 v[132:133], 7, v[202:203]
	v_lshl_add_u64 v[136:137], v[142:143], 0, v[132:133]
	s_waitcnt vmcnt(3)
	v_mov_b64_e32 v[132:133], v[238:239]
	v_mov_b64_e32 v[134:135], v[240:241]
	global_load_dwordx4 v[238:241], v[248:249], off offset:2064
	s_nop 0
	s_waitcnt vmcnt(3)
	v_mov_b64_e32 v[136:137], v[242:243]
	v_mov_b64_e32 v[138:139], v[244:245]
	global_load_dwordx4 v[242:245], v[248:249], off offset:2048
	s_waitcnt lgkmcnt(0)
	v_pk_add_f32 v[132:133], v[132:133], v[134:135]
	s_waitcnt lgkmcnt(0)
	v_pk_add_f32 v[136:137], v[136:137], v[138:139]
	s_nop 0
	v_pk_add_f32 v[132:133], v[136:137], v[132:133]
	ds_bpermute_b32 v134, v163, v132
	ds_bpermute_b32 v135, v163, v133
	s_waitcnt lgkmcnt(0)
	v_pk_add_f32 v[132:133], v[132:133], v[134:135]
	ds_bpermute_b32 v134, v167, v132
	ds_bpermute_b32 v135, v167, v133
	s_waitcnt lgkmcnt(0)
	v_pk_add_f32 v[132:133], v[132:133], v[134:135]
	s_nop 0
	v_pk_mul_f32 v[180:181], v[132:133], s[82:83] op_sel_hi:[1,0]
	s_nop 0
	v_fma_f32 v132, -v180, v180, v181
	v_max_f32_e32 v132, 0, v132
	v_add_f32_e32 v132, 0x3727c5ac, v132
	v_rsq_f32_e32 v182, v132
	v_lshlrev_b64 v[132:133], 7, v[206:207]
	v_lshl_add_u64 v[136:137], v[142:143], 0, v[132:133]
	s_waitcnt vmcnt(3)
	v_mov_b64_e32 v[132:133], v[214:215]
	v_mov_b64_e32 v[134:135], v[216:217]
	s_nop 0
	s_waitcnt vmcnt(2)
	v_mov_b64_e32 v[136:137], v[234:235]
	v_mov_b64_e32 v[138:139], v[236:237]
	s_waitcnt lgkmcnt(0)
	v_pk_add_f32 v[132:133], v[132:133], v[134:135]
	s_waitcnt lgkmcnt(0)
	v_pk_add_f32 v[136:137], v[136:137], v[138:139]
	s_nop 0
	v_pk_add_f32 v[132:133], v[136:137], v[132:133]
	ds_bpermute_b32 v134, v163, v132
	ds_bpermute_b32 v135, v163, v133
	s_waitcnt lgkmcnt(0)
	v_pk_add_f32 v[132:133], v[132:133], v[134:135]
	ds_bpermute_b32 v134, v167, v132
	ds_bpermute_b32 v135, v167, v133
	s_waitcnt lgkmcnt(0)
	v_pk_add_f32 v[132:133], v[132:133], v[134:135]
	s_nop 0
	v_pk_mul_f32 v[184:185], v[132:133], s[82:83] op_sel_hi:[1,0]
	s_nop 0
	v_fma_f32 v132, -v184, v184, v185
	v_max_f32_e32 v132, 0, v132
	v_add_f32_e32 v132, 0x3727c5ac, v132
	v_rsq_f32_e32 v186, v132
	v_lshlrev_b64 v[132:133], 7, v[204:205]
	v_lshl_add_u64 v[136:137], v[142:143], 0, v[132:133]
	s_waitcnt vmcnt(1)
	v_mov_b64_e32 v[132:133], v[238:239]
	v_mov_b64_e32 v[134:135], v[240:241]
	s_nop 0
	s_waitcnt vmcnt(0)
	v_mov_b64_e32 v[136:137], v[242:243]
	v_mov_b64_e32 v[138:139], v[244:245]
	s_waitcnt lgkmcnt(0)
	v_pk_add_f32 v[132:133], v[132:133], v[134:135]
	s_waitcnt lgkmcnt(0)
	v_pk_add_f32 v[136:137], v[136:137], v[138:139]
	s_nop 0
	v_pk_add_f32 v[132:133], v[136:137], v[132:133]
	ds_bpermute_b32 v134, v163, v132
	ds_bpermute_b32 v135, v163, v133
	v_lshlrev_b64 v[136:137], 2, v[208:209]
	s_waitcnt lgkmcnt(0)
	v_pk_add_f32 v[132:133], v[132:133], v[134:135]
	ds_bpermute_b32 v134, v167, v132
	ds_bpermute_b32 v135, v167, v133
	s_waitcnt lgkmcnt(0)
	v_pk_add_f32 v[132:133], v[132:133], v[134:135]
	s_nop 0
	v_pk_mul_f32 v[188:189], v[132:133], s[82:83] op_sel_hi:[1,0]
	s_nop 0
	v_fma_f32 v132, -v188, v188, v189
	v_max_f32_e32 v132, 0, v132
	v_add_f32_e32 v132, 0x3727c5ac, v132
	v_rsq_f32_e32 v190, v132
	v_lshl_add_u64 v[132:133], s[42:43], 0, v[136:137]
	ds_read_b128 v[132:135], v255
	v_lshl_add_u64 v[136:137], s[46:47], 0, v[136:137]
	ds_read_b128 v[136:139], v255 offset:256
	s_waitcnt lgkmcnt(0)
; __device__ __forceinline__ u32x2 pk4(f32x4 v) { u32x2 r; r.x = pk2(v.x, v.y); r.y = pk2(v.z, v.w); return r; }
;     __device__ __forceinline__ void operator()(const f32x4 (&acc)[2][2][4][2], const pg8::Unit& u, int wr, int wc, int fr, int fq) const {
;     ...
;         for (int bj = 0; bj < 2; ++bj)
; #pragma unroll
;             for (int n = 0; n < 2; ++n) {
;                 const int col = u.pn * 256 + bj * 128 + wc * 32 + n * 16 + fq * 4;
;                 f32x4 c1v = (f32x4){0.f, 0.f, 0.f, 0.f}, c2v = c1v;
;                 if (fold) { c1v = *(const f32x4*)(c1 + col); c2v = *(const f32x4*)(c2 + col); }
; #pragma unroll
;                 for (int ai = 0; ai < 2; ++ai)
; #pragma unroll
;                     for (int m = 0; m < 4; ++m) {
;                         f32x4 v = acc[ai][bj][m][n];
;                         if (fold) v = (v - c1v * mu[ai][m]) * rs[ai][m] + c2v;
;                         f(u.pm * 256 + ai * 128 + wr * 64 + m * 16 + fr, col, v, fq, ps1[ai][m], ps2[ai][m]);
;                     }
;     __device__ __forceinline__ void operator()(int row, int col, f32x4 v, int, float&, float&) const { *(u32x2*)(O + (size_t)row * ldc + col) = pk4(v * s); }
	v_pk_fma_f32 v[128:129], v[148:149], v[132:133], v[128:129] op_sel_hi:[0,1,1] neg_lo:[1,0,0] neg_hi:[1,0,0]
	v_pk_fma_f32 v[130:131], v[148:149], v[134:135], v[130:131] op_sel_hi:[0,1,1] neg_lo:[1,0,0] neg_hi:[1,0,0]
	s_waitcnt lgkmcnt(0)
	v_pk_fma_f32 v[128:129], v[150:151], v[128:129], v[136:137] op_sel_hi:[0,1,1]
	v_pk_fma_f32 v[130:131], v[150:151], v[130:131], v[138:139] op_sel_hi:[0,1,1]
	v_pk_mul_f32 v[128:129], v[128:129], s[84:85] op_sel_hi:[1,0]
	v_pk_mul_f32 v[130:131], v[130:131], s[84:85] op_sel_hi:[1,0]
	v_cvt_pk_bf16_f32 v168, v128, v129
	v_lshlrev_b64 v[128:129], 11, v[192:193]
	v_pk_fma_f32 v[126:127], v[152:153], v[134:135], v[126:127] op_sel_hi:[0,1,1] neg_lo:[1,0,0] neg_hi:[1,0,0]
	v_pk_fma_f32 v[122:123], v[156:157], v[134:135], v[122:123] op_sel_hi:[0,1,1] neg_lo:[1,0,0] neg_hi:[1,0,0]
	v_pk_fma_f32 v[118:119], v[160:161], v[134:135], v[118:119] op_sel_hi:[0,1,1] neg_lo:[1,0,0] neg_hi:[1,0,0]
	v_pk_fma_f32 v[114:115], v[164:165], v[134:135], v[114:115] op_sel_hi:[0,1,1] neg_lo:[1,0,0] neg_hi:[1,0,0]
	v_pk_fma_f32 v[106:107], v[180:181], v[134:135], v[106:107] op_sel_hi:[0,1,1] neg_lo:[1,0,0] neg_hi:[1,0,0]
	v_pk_fma_f32 v[98:99], v[184:185], v[134:135], v[98:99] op_sel_hi:[0,1,1] neg_lo:[1,0,0] neg_hi:[1,0,0]
	v_cvt_pk_bf16_f32 v169, v130, v131
	v_lshl_add_u64 v[128:129], s[0:1], 0, v[128:129]
	v_lshlrev_b64 v[130:131], 1, v[208:209]
	v_pk_fma_f32 v[126:127], v[154:155], v[126:127], v[138:139] op_sel_hi:[0,1,1]
	v_pk_fma_f32 v[122:123], v[158:159], v[122:123], v[138:139] op_sel_hi:[0,1,1]
	v_pk_fma_f32 v[118:119], v[162:163], v[118:119], v[138:139] op_sel_hi:[0,1,1]
	v_pk_fma_f32 v[114:115], v[166:167], v[114:115], v[138:139] op_sel_hi:[0,1,1]
	v_pk_fma_f32 v[106:107], v[182:183], v[106:107], v[138:139] op_sel_hi:[0,1,1]
	v_pk_fma_f32 v[98:99], v[186:187], v[98:99], v[138:139] op_sel_hi:[0,1,1]
	v_lshl_add_u64 v[128:129], v[128:129], 0, v[130:131]
	v_pk_mul_f32 v[126:127], v[126:127], s[84:85] op_sel_hi:[1,0]
	v_pk_mul_f32 v[122:123], v[122:123], s[84:85] op_sel_hi:[1,0]
	v_pk_mul_f32 v[118:119], v[118:119], s[84:85] op_sel_hi:[1,0]
	v_pk_mul_f32 v[114:115], v[114:115], s[84:85] op_sel_hi:[1,0]
	v_pk_mul_f32 v[106:107], v[106:107], s[84:85] op_sel_hi:[1,0]
	v_pk_mul_f32 v[98:99], v[98:99], s[84:85] op_sel_hi:[1,0]
	global_store_dwordx2 v[128:129], v[168:169], off
	v_cvt_pk_bf16_f32 v169, v126, v127
	v_cvt_pk_bf16_f32 v127, v122, v123
	v_cvt_pk_bf16_f32 v123, v118, v119
	v_cvt_pk_bf16_f32 v119, v114, v115
	v_cvt_pk_bf16_f32 v115, v106, v107
	v_cvt_pk_bf16_f32 v107, v98, v99
	v_xor_b32_e32 v99, 0x80000000, v135
	v_xor_b32_e32 v98, 0x80000000, v134
	v_pk_fma_f32 v[124:125], v[152:153], v[132:133], v[124:125] op_sel_hi:[0,1,1] neg_lo:[1,0,0] neg_hi:[1,0,0]
	v_pk_fma_f32 v[120:121], v[156:157], v[132:133], v[120:121] op_sel_hi:[0,1,1] neg_lo:[1,0,0] neg_hi:[1,0,0]
	v_pk_fma_f32 v[116:117], v[160:161], v[132:133], v[116:117] op_sel_hi:[0,1,1] neg_lo:[1,0,0] neg_hi:[1,0,0]
	v_pk_fma_f32 v[112:113], v[164:165], v[132:133], v[112:113] op_sel_hi:[0,1,1] neg_lo:[1,0,0] neg_hi:[1,0,0]
	v_pk_fma_f32 v[104:105], v[180:181], v[132:133], v[104:105] op_sel_hi:[0,1,1] neg_lo:[1,0,0] neg_hi:[1,0,0]
	v_pk_fma_f32 v[96:97], v[184:185], v[132:133], v[96:97] op_sel_hi:[0,1,1] neg_lo:[1,0,0] neg_hi:[1,0,0]
	v_pk_fma_f32 v[90:91], v[98:99], v[188:189], v[90:91] op_sel_hi:[1,0,1]
	v_pk_fma_f32 v[88:89], v[132:133], v[188:189], v[88:89] op_sel_hi:[1,0,1] neg_lo:[1,0,0] neg_hi:[1,0,0]
	v_pk_fma_f32 v[124:125], v[154:155], v[124:125], v[136:137] op_sel_hi:[0,1,1]
	v_pk_fma_f32 v[120:121], v[158:159], v[120:121], v[136:137] op_sel_hi:[0,1,1]
	v_pk_fma_f32 v[116:117], v[162:163], v[116:117], v[136:137] op_sel_hi:[0,1,1]
	v_pk_fma_f32 v[112:113], v[166:167], v[112:113], v[136:137] op_sel_hi:[0,1,1]
	v_pk_fma_f32 v[104:105], v[182:183], v[104:105], v[136:137] op_sel_hi:[0,1,1]
	v_pk_fma_f32 v[96:97], v[186:187], v[96:97], v[136:137] op_sel_hi:[0,1,1]
	v_pk_fma_f32 v[88:89], v[88:89], v[190:191], v[136:137] op_sel_hi:[1,0,1]
	v_pk_fma_f32 v[90:91], v[90:91], v[190:191], v[138:139] op_sel_hi:[1,0,1]
	v_pk_mul_f32 v[124:125], v[124:125], s[84:85] op_sel_hi:[1,0]
	v_pk_mul_f32 v[120:121], v[120:121], s[84:85] op_sel_hi:[1,0]
	v_pk_mul_f32 v[116:117], v[116:117], s[84:85] op_sel_hi:[1,0]
	v_pk_mul_f32 v[112:113], v[112:113], s[84:85] op_sel_hi:[1,0]
	v_pk_mul_f32 v[104:105], v[104:105], s[84:85] op_sel_hi:[1,0]
	v_pk_mul_f32 v[96:97], v[96:97], s[84:85] op_sel_hi:[1,0]
	v_pk_mul_f32 v[90:91], v[90:91], s[84:85] op_sel_hi:[1,0]
	v_pk_mul_f32 v[88:89], v[88:89], s[84:85] op_sel_hi:[1,0]
	v_cvt_pk_bf16_f32 v168, v124, v125
	v_lshlrev_b64 v[124:125], 11, v[194:195]
	v_cvt_pk_bf16_f32 v126, v120, v121
	v_lshlrev_b64 v[120:121], 11, v[196:197]
	v_cvt_pk_bf16_f32 v122, v116, v117
	v_lshlrev_b64 v[116:117], 11, v[198:199]
	v_cvt_pk_bf16_f32 v118, v112, v113
	v_lshlrev_b64 v[112:113], 11, v[200:201]
	v_cvt_pk_bf16_f32 v114, v104, v105
	v_lshlrev_b64 v[104:105], 11, v[202:203]
	v_cvt_pk_bf16_f32 v106, v96, v97
	v_lshlrev_b64 v[96:97], 11, v[206:207]
	v_cvt_pk_bf16_f32 v98, v88, v89
	v_cvt_pk_bf16_f32 v99, v90, v91
	v_lshlrev_b64 v[88:89], 11, v[204:205]
	v_add_u32_e32 v90, 16, v208
	v_lshl_add_u64 v[124:125], s[0:1], 0, v[124:125]
	v_lshl_add_u64 v[120:121], s[0:1], 0, v[120:121]
	v_lshl_add_u64 v[116:117], s[0:1], 0, v[116:117]
	v_lshl_add_u64 v[112:113], s[0:1], 0, v[112:113]
	v_lshl_add_u64 v[104:105], s[0:1], 0, v[104:105]
	v_lshl_add_u64 v[96:97], s[0:1], 0, v[96:97]
	v_lshl_add_u64 v[88:89], s[0:1], 0, v[88:89]
	v_ashrrev_i32_e32 v91, 31, v90
	v_lshl_add_u64 v[124:125], v[124:125], 0, v[130:131]
	v_lshl_add_u64 v[120:121], v[120:121], 0, v[130:131]
	v_lshl_add_u64 v[116:117], v[116:117], 0, v[130:131]
	v_lshl_add_u64 v[112:113], v[112:113], 0, v[130:131]
	v_lshl_add_u64 v[104:105], v[104:105], 0, v[130:131]
	v_lshl_add_u64 v[96:97], v[96:97], 0, v[130:131]
	v_lshl_add_u64 v[88:89], v[88:89], 0, v[130:131]
	v_lshlrev_b64 v[90:91], 2, v[90:91]
	global_store_dwordx2 v[124:125], v[168:169], off
	global_store_dwordx2 v[120:121], v[126:127], off
	global_store_dwordx2 v[116:117], v[122:123], off
	global_store_dwordx2 v[112:113], v[118:119], off
	global_store_dwordx2 v[104:105], v[114:115], off
	global_store_dwordx2 v[96:97], v[106:107], off
	global_store_dwordx2 v[88:89], v[98:99], off
	v_lshl_add_u64 v[98:99], s[42:43], 0, v[90:91]
	ds_read_b128 v[130:133], v255 offset:64
	v_lshl_add_u64 v[90:91], s[46:47], 0, v[90:91]
	ds_read_b128 v[134:137], v255 offset:320
	s_mov_b64 s[0:1], -1
	s_waitcnt lgkmcnt(0)
; __device__ __forceinline__ u32x2 pk4(f32x4 v) { u32x2 r; r.x = pk2(v.x, v.y); r.y = pk2(v.z, v.w); return r; }
;     __device__ __forceinline__ void operator()(const f32x4 (&acc)[2][2][4][2], const pg8::Unit& u, int wr, int wc, int fr, int fq) const {
;     ...
;         for (int bj = 0; bj < 2; ++bj)
; #pragma unroll
;             for (int n = 0; n < 2; ++n) {
;                 const int col = u.pn * 256 + bj * 128 + wc * 32 + n * 16 + fq * 4;
;                 f32x4 c1v = (f32x4){0.f, 0.f, 0.f, 0.f}, c2v = c1v;
;                 if (fold) { c1v = *(const f32x4*)(c1 + col); c2v = *(const f32x4*)(c2 + col); }
; #pragma unroll
;                 for (int ai = 0; ai < 2; ++ai)
; #pragma unroll
;                     for (int m = 0; m < 4; ++m) {
;                         f32x4 v = acc[ai][bj][m][n];
;                         if (fold) v = (v - c1v * mu[ai][m]) * rs[ai][m] + c2v;
;                         f(u.pm * 256 + ai * 128 + wr * 64 + m * 16 + fr, col, v, fq, ps1[ai][m], ps2[ai][m]);
;                     }
;     __device__ __forceinline__ void operator()(int row, int col, f32x4 v, int, float&, float&) const { *(u32x2*)(O + (size_t)row * ldc + col) = pk4(v * s); }
	v_pk_fma_f32 v[90:91], v[148:149], v[132:133], v[110:111] op_sel_hi:[0,1,1] neg_lo:[1,0,0] neg_hi:[1,0,0]
	v_pk_fma_f32 v[98:99], v[148:149], v[130:131], v[108:109] op_sel_hi:[0,1,1] neg_lo:[1,0,0] neg_hi:[1,0,0]
	s_waitcnt lgkmcnt(0)
	v_pk_fma_f32 v[98:99], v[150:151], v[98:99], v[134:135] op_sel_hi:[0,1,1]
	v_pk_fma_f32 v[90:91], v[150:151], v[90:91], v[136:137] op_sel_hi:[0,1,1]
	v_pk_mul_f32 v[90:91], v[90:91], s[84:85] op_sel_hi:[1,0]
	v_pk_mul_f32 v[98:99], v[98:99], s[84:85] op_sel_hi:[1,0]
	v_pk_fma_f32 v[62:63], v[188:189], v[132:133], v[62:63] op_sel_hi:[0,1,1] neg_lo:[1,0,0] neg_hi:[1,0,0]
	v_cvt_pk_bf16_f32 v98, v98, v99
	v_cvt_pk_bf16_f32 v99, v90, v91
	global_store_dwordx2 v[128:129], v[98:99], off offset:32
	v_pk_fma_f32 v[90:91], v[152:153], v[132:133], v[102:103] op_sel_hi:[0,1,1] neg_lo:[1,0,0] neg_hi:[1,0,0]
	v_pk_fma_f32 v[98:99], v[152:153], v[130:131], v[100:101] op_sel_hi:[0,1,1] neg_lo:[1,0,0] neg_hi:[1,0,0]
	v_pk_fma_f32 v[60:61], v[188:189], v[130:131], v[60:61] op_sel_hi:[0,1,1] neg_lo:[1,0,0] neg_hi:[1,0,0]
	v_pk_fma_f32 v[98:99], v[154:155], v[98:99], v[134:135] op_sel_hi:[0,1,1]
	v_pk_fma_f32 v[90:91], v[154:155], v[90:91], v[136:137] op_sel_hi:[0,1,1]
	v_pk_fma_f32 v[60:61], v[190:191], v[60:61], v[134:135] op_sel_hi:[0,1,1]
	v_pk_fma_f32 v[62:63], v[190:191], v[62:63], v[136:137] op_sel_hi:[0,1,1]
	v_pk_mul_f32 v[90:91], v[90:91], s[84:85] op_sel_hi:[1,0]
	v_pk_mul_f32 v[98:99], v[98:99], s[84:85] op_sel_hi:[1,0]
	v_pk_fma_f32 v[70:71], v[184:185], v[132:133], v[70:71] op_sel_hi:[0,1,1] neg_lo:[1,0,0] neg_hi:[1,0,0]
	v_pk_fma_f32 v[68:69], v[184:185], v[130:131], v[68:69] op_sel_hi:[0,1,1] neg_lo:[1,0,0] neg_hi:[1,0,0]
	v_pk_mul_f32 v[62:63], v[62:63], s[84:85] op_sel_hi:[1,0]
	v_pk_mul_f32 v[60:61], v[60:61], s[84:85] op_sel_hi:[1,0]
	v_cvt_pk_bf16_f32 v98, v98, v99
	v_cvt_pk_bf16_f32 v99, v90, v91
	v_pk_fma_f32 v[90:91], v[156:157], v[132:133], v[94:95] op_sel_hi:[0,1,1] neg_lo:[1,0,0] neg_hi:[1,0,0]
	v_pk_fma_f32 v[92:93], v[156:157], v[130:131], v[92:93] op_sel_hi:[0,1,1] neg_lo:[1,0,0] neg_hi:[1,0,0]
	v_pk_fma_f32 v[86:87], v[160:161], v[132:133], v[86:87] op_sel_hi:[0,1,1] neg_lo:[1,0,0] neg_hi:[1,0,0]
	v_pk_fma_f32 v[84:85], v[160:161], v[130:131], v[84:85] op_sel_hi:[0,1,1] neg_lo:[1,0,0] neg_hi:[1,0,0]
	v_pk_fma_f32 v[82:83], v[164:165], v[132:133], v[82:83] op_sel_hi:[0,1,1] neg_lo:[1,0,0] neg_hi:[1,0,0]
	v_pk_fma_f32 v[80:81], v[164:165], v[130:131], v[80:81] op_sel_hi:[0,1,1] neg_lo:[1,0,0] neg_hi:[1,0,0]
	v_pk_fma_f32 v[78:79], v[180:181], v[132:133], v[78:79] op_sel_hi:[0,1,1] neg_lo:[1,0,0] neg_hi:[1,0,0]
	v_pk_fma_f32 v[76:77], v[180:181], v[130:131], v[76:77] op_sel_hi:[0,1,1] neg_lo:[1,0,0] neg_hi:[1,0,0]
	v_pk_fma_f32 v[68:69], v[186:187], v[68:69], v[134:135] op_sel_hi:[0,1,1]
	v_pk_fma_f32 v[70:71], v[186:187], v[70:71], v[136:137] op_sel_hi:[0,1,1]
	v_cvt_pk_bf16_f32 v60, v60, v61
	v_cvt_pk_bf16_f32 v61, v62, v63
	v_pk_fma_f32 v[92:93], v[158:159], v[92:93], v[134:135] op_sel_hi:[0,1,1]
	v_pk_fma_f32 v[90:91], v[158:159], v[90:91], v[136:137] op_sel_hi:[0,1,1]
	v_pk_fma_f32 v[84:85], v[162:163], v[84:85], v[134:135] op_sel_hi:[0,1,1]
	v_pk_fma_f32 v[86:87], v[162:163], v[86:87], v[136:137] op_sel_hi:[0,1,1]
	v_pk_fma_f32 v[80:81], v[166:167], v[80:81], v[134:135] op_sel_hi:[0,1,1]
	v_pk_fma_f32 v[82:83], v[166:167], v[82:83], v[136:137] op_sel_hi:[0,1,1]
	v_pk_fma_f32 v[76:77], v[182:183], v[76:77], v[134:135] op_sel_hi:[0,1,1]
	v_pk_fma_f32 v[78:79], v[182:183], v[78:79], v[136:137] op_sel_hi:[0,1,1]
	v_pk_mul_f32 v[70:71], v[70:71], s[84:85] op_sel_hi:[1,0]
	v_pk_mul_f32 v[68:69], v[68:69], s[84:85] op_sel_hi:[1,0]
	global_store_dwordx2 v[88:89], v[60:61], off offset:32
	v_add_u32_e32 v60, 0x80, v208
	v_pk_mul_f32 v[90:91], v[90:91], s[84:85] op_sel_hi:[1,0]
	v_pk_mul_f32 v[92:93], v[92:93], s[84:85] op_sel_hi:[1,0]
	v_pk_mul_f32 v[86:87], v[86:87], s[84:85] op_sel_hi:[1,0]
	v_pk_mul_f32 v[84:85], v[84:85], s[84:85] op_sel_hi:[1,0]
	v_pk_mul_f32 v[82:83], v[82:83], s[84:85] op_sel_hi:[1,0]
	v_pk_mul_f32 v[80:81], v[80:81], s[84:85] op_sel_hi:[1,0]
	v_pk_mul_f32 v[78:79], v[78:79], s[84:85] op_sel_hi:[1,0]
	v_pk_mul_f32 v[76:77], v[76:77], s[84:85] op_sel_hi:[1,0]
	v_cvt_pk_bf16_f32 v68, v68, v69
	v_cvt_pk_bf16_f32 v69, v70, v71
	v_ashrrev_i32_e32 v61, 31, v60
	v_cvt_pk_bf16_f32 v92, v92, v93
	v_cvt_pk_bf16_f32 v93, v90, v91
	v_cvt_pk_bf16_f32 v84, v84, v85
	v_cvt_pk_bf16_f32 v85, v86, v87
	v_cvt_pk_bf16_f32 v80, v80, v81
	v_cvt_pk_bf16_f32 v81, v82, v83
	v_cvt_pk_bf16_f32 v76, v76, v77
	v_cvt_pk_bf16_f32 v77, v78, v79
	global_store_dwordx2 v[96:97], v[68:69], off offset:32
	v_lshlrev_b64 v[68:69], 2, v[60:61]
	global_store_dwordx2 v[124:125], v[98:99], off offset:32
	global_store_dwordx2 v[120:121], v[92:93], off offset:32
	global_store_dwordx2 v[116:117], v[84:85], off offset:32
	global_store_dwordx2 v[112:113], v[80:81], off offset:32
	global_store_dwordx2 v[104:105], v[76:77], off offset:32
	v_lshl_add_u64 v[60:61], s[42:43], 0, v[68:69]
	ds_read_b128 v[60:63], v255 offset:128
	v_lshl_add_u64 v[68:69], s[46:47], 0, v[68:69]
	ds_read_b128 v[68:71], v255 offset:384
	s_waitcnt lgkmcnt(0)
	v_pk_fma_f32 v[26:27], v[188:189], v[62:63], v[26:27] op_sel_hi:[0,1,1] neg_lo:[1,0,0] neg_hi:[1,0,0]
	v_pk_fma_f32 v[24:25], v[188:189], v[60:61], v[24:25] op_sel_hi:[0,1,1] neg_lo:[1,0,0] neg_hi:[1,0,0]
	s_waitcnt lgkmcnt(0)
; __device__ __forceinline__ u32x2 pk4(f32x4 v) { u32x2 r; r.x = pk2(v.x, v.y); r.y = pk2(v.z, v.w); return r; }
;     __device__ __forceinline__ void operator()(const f32x4 (&acc)[2][2][4][2], const pg8::Unit& u, int wr, int wc, int fr, int fq) const {
;     ...
;         for (int bj = 0; bj < 2; ++bj)
; #pragma unroll
;             for (int n = 0; n < 2; ++n) {
;                 const int col = u.pn * 256 + bj * 128 + wc * 32 + n * 16 + fq * 4;
;                 f32x4 c1v = (f32x4){0.f, 0.f, 0.f, 0.f}, c2v = c1v;
;                 if (fold) { c1v = *(const f32x4*)(c1 + col); c2v = *(const f32x4*)(c2 + col); }
; #pragma unroll
;                 for (int ai = 0; ai < 2; ++ai)
; #pragma unroll
;                     for (int m = 0; m < 4; ++m) {
;                         f32x4 v = acc[ai][bj][m][n];
;                         if (fold) v = (v - c1v * mu[ai][m]) * rs[ai][m] + c2v;
;                         f(u.pm * 256 + ai * 128 + wr * 64 + m * 16 + fr, col, v, fq, ps1[ai][m], ps2[ai][m]);
;                     }
;     __device__ __forceinline__ void operator()(int row, int col, f32x4 v, int, float&, float&) const { *(u32x2*)(O + (size_t)row * ldc + col) = pk4(v * s); }
	v_pk_fma_f32 v[24:25], v[190:191], v[24:25], v[68:69] op_sel_hi:[0,1,1]
	v_pk_fma_f32 v[26:27], v[190:191], v[26:27], v[70:71] op_sel_hi:[0,1,1]
	v_pk_fma_f32 v[34:35], v[184:185], v[62:63], v[34:35] op_sel_hi:[0,1,1] neg_lo:[1,0,0] neg_hi:[1,0,0]
	v_pk_fma_f32 v[32:33], v[184:185], v[60:61], v[32:33] op_sel_hi:[0,1,1] neg_lo:[1,0,0] neg_hi:[1,0,0]
	v_pk_mul_f32 v[26:27], v[26:27], s[84:85] op_sel_hi:[1,0]
	v_pk_mul_f32 v[24:25], v[24:25], s[84:85] op_sel_hi:[1,0]
	v_pk_fma_f32 v[74:75], v[148:149], v[62:63], v[74:75] op_sel_hi:[0,1,1] neg_lo:[1,0,0] neg_hi:[1,0,0]
	v_pk_fma_f32 v[72:73], v[148:149], v[60:61], v[72:73] op_sel_hi:[0,1,1] neg_lo:[1,0,0] neg_hi:[1,0,0]
	v_pk_fma_f32 v[66:67], v[152:153], v[62:63], v[66:67] op_sel_hi:[0,1,1] neg_lo:[1,0,0] neg_hi:[1,0,0]
	v_pk_fma_f32 v[64:65], v[152:153], v[60:61], v[64:65] op_sel_hi:[0,1,1] neg_lo:[1,0,0] neg_hi:[1,0,0]
	v_pk_fma_f32 v[58:59], v[156:157], v[62:63], v[58:59] op_sel_hi:[0,1,1] neg_lo:[1,0,0] neg_hi:[1,0,0]
	v_pk_fma_f32 v[56:57], v[156:157], v[60:61], v[56:57] op_sel_hi:[0,1,1] neg_lo:[1,0,0] neg_hi:[1,0,0]
	v_pk_fma_f32 v[54:55], v[160:161], v[62:63], v[54:55] op_sel_hi:[0,1,1] neg_lo:[1,0,0] neg_hi:[1,0,0]
	v_pk_fma_f32 v[52:53], v[160:161], v[60:61], v[52:53] op_sel_hi:[0,1,1] neg_lo:[1,0,0] neg_hi:[1,0,0]
	v_pk_fma_f32 v[50:51], v[164:165], v[62:63], v[50:51] op_sel_hi:[0,1,1] neg_lo:[1,0,0] neg_hi:[1,0,0]
	v_pk_fma_f32 v[48:49], v[164:165], v[60:61], v[48:49] op_sel_hi:[0,1,1] neg_lo:[1,0,0] neg_hi:[1,0,0]
	v_pk_fma_f32 v[42:43], v[180:181], v[62:63], v[42:43] op_sel_hi:[0,1,1] neg_lo:[1,0,0] neg_hi:[1,0,0]
	v_pk_fma_f32 v[40:41], v[180:181], v[60:61], v[40:41] op_sel_hi:[0,1,1] neg_lo:[1,0,0] neg_hi:[1,0,0]
	v_pk_fma_f32 v[32:33], v[186:187], v[32:33], v[68:69] op_sel_hi:[0,1,1]
	v_pk_fma_f32 v[34:35], v[186:187], v[34:35], v[70:71] op_sel_hi:[0,1,1]
	v_cvt_pk_bf16_f32 v24, v24, v25
	v_cvt_pk_bf16_f32 v25, v26, v27
	v_pk_fma_f32 v[72:73], v[150:151], v[72:73], v[68:69] op_sel_hi:[0,1,1]
	v_pk_fma_f32 v[74:75], v[150:151], v[74:75], v[70:71] op_sel_hi:[0,1,1]
	v_pk_fma_f32 v[64:65], v[154:155], v[64:65], v[68:69] op_sel_hi:[0,1,1]
	v_pk_fma_f32 v[66:67], v[154:155], v[66:67], v[70:71] op_sel_hi:[0,1,1]
	v_pk_fma_f32 v[56:57], v[158:159], v[56:57], v[68:69] op_sel_hi:[0,1,1]
	v_pk_fma_f32 v[58:59], v[158:159], v[58:59], v[70:71] op_sel_hi:[0,1,1]
	v_pk_fma_f32 v[52:53], v[162:163], v[52:53], v[68:69] op_sel_hi:[0,1,1]
	v_pk_fma_f32 v[54:55], v[162:163], v[54:55], v[70:71] op_sel_hi:[0,1,1]
	v_pk_fma_f32 v[48:49], v[166:167], v[48:49], v[68:69] op_sel_hi:[0,1,1]
	v_pk_fma_f32 v[50:51], v[166:167], v[50:51], v[70:71] op_sel_hi:[0,1,1]
	v_pk_fma_f32 v[40:41], v[182:183], v[40:41], v[68:69] op_sel_hi:[0,1,1]
	v_pk_fma_f32 v[42:43], v[182:183], v[42:43], v[70:71] op_sel_hi:[0,1,1]
	v_pk_mul_f32 v[34:35], v[34:35], s[84:85] op_sel_hi:[1,0]
	v_pk_mul_f32 v[32:33], v[32:33], s[84:85] op_sel_hi:[1,0]
	global_store_dwordx2 v[88:89], v[24:25], off offset:256
	v_add_u32_e32 v24, 0x90, v208
	v_pk_mul_f32 v[74:75], v[74:75], s[84:85] op_sel_hi:[1,0]
	v_pk_mul_f32 v[72:73], v[72:73], s[84:85] op_sel_hi:[1,0]
	v_pk_mul_f32 v[66:67], v[66:67], s[84:85] op_sel_hi:[1,0]
	v_pk_mul_f32 v[64:65], v[64:65], s[84:85] op_sel_hi:[1,0]
	v_pk_mul_f32 v[58:59], v[58:59], s[84:85] op_sel_hi:[1,0]
	v_pk_mul_f32 v[56:57], v[56:57], s[84:85] op_sel_hi:[1,0]
	v_pk_mul_f32 v[54:55], v[54:55], s[84:85] op_sel_hi:[1,0]
	v_pk_mul_f32 v[52:53], v[52:53], s[84:85] op_sel_hi:[1,0]
	v_pk_mul_f32 v[50:51], v[50:51], s[84:85] op_sel_hi:[1,0]
	v_pk_mul_f32 v[48:49], v[48:49], s[84:85] op_sel_hi:[1,0]
	v_pk_mul_f32 v[42:43], v[42:43], s[84:85] op_sel_hi:[1,0]
	v_pk_mul_f32 v[40:41], v[40:41], s[84:85] op_sel_hi:[1,0]
	v_cvt_pk_bf16_f32 v32, v32, v33
	v_cvt_pk_bf16_f32 v33, v34, v35
	v_ashrrev_i32_e32 v25, 31, v24
	v_cvt_pk_bf16_f32 v72, v72, v73
	v_cvt_pk_bf16_f32 v73, v74, v75
	v_cvt_pk_bf16_f32 v64, v64, v65
	v_cvt_pk_bf16_f32 v65, v66, v67
	v_cvt_pk_bf16_f32 v56, v56, v57
	v_cvt_pk_bf16_f32 v57, v58, v59
	v_cvt_pk_bf16_f32 v52, v52, v53
	v_cvt_pk_bf16_f32 v53, v54, v55
	v_cvt_pk_bf16_f32 v48, v48, v49
	v_cvt_pk_bf16_f32 v49, v50, v51
	v_cvt_pk_bf16_f32 v40, v40, v41
	v_cvt_pk_bf16_f32 v41, v42, v43
	global_store_dwordx2 v[96:97], v[32:33], off offset:256
	v_lshlrev_b64 v[32:33], 2, v[24:25]
	global_store_dwordx2 v[128:129], v[72:73], off offset:256
	global_store_dwordx2 v[124:125], v[64:65], off offset:256
	global_store_dwordx2 v[120:121], v[56:57], off offset:256
	global_store_dwordx2 v[116:117], v[52:53], off offset:256
	global_store_dwordx2 v[112:113], v[48:49], off offset:256
	global_store_dwordx2 v[104:105], v[40:41], off offset:256
	v_lshl_add_u64 v[24:25], s[42:43], 0, v[32:33]
	ds_read_b128 v[24:27], v255 offset:192
	v_lshl_add_u64 v[32:33], s[46:47], 0, v[32:33]
	ds_read_b128 v[32:35], v255 offset:448
	s_waitcnt lgkmcnt(0)
; __device__ __forceinline__ u32x2 pk4(f32x4 v) { u32x2 r; r.x = pk2(v.x, v.y); r.y = pk2(v.z, v.w); return r; }
;     __device__ __forceinline__ void operator()(const f32x4 (&acc)[2][2][4][2], const pg8::Unit& u, int wr, int wc, int fr, int fq) const {
;     ...
; #pragma unroll
;                 for (int ai = 0; ai < 2; ++ai)
; #pragma unroll
;                     for (int m = 0; m < 4; ++m) {
;                         f32x4 v = acc[ai][bj][m][n];
;                         if (fold) v = (v - c1v * mu[ai][m]) * rs[ai][m] + c2v;
;                         f(u.pm * 256 + ai * 128 + wr * 64 + m * 16 + fr, col, v, fq, ps1[ai][m], ps2[ai][m]);
;                     }
;     __device__ __forceinline__ void operator()(int row, int col, f32x4 v, int, float&, float&) const { *(u32x2*)(O + (size_t)row * ldc + col) = pk4(v * s); }
	v_pk_fma_f32 v[40:41], v[148:149], v[26:27], v[46:47] op_sel_hi:[0,1,1] neg_lo:[1,0,0] neg_hi:[1,0,0]
	v_pk_fma_f32 v[42:43], v[148:149], v[24:25], v[44:45] op_sel_hi:[0,1,1] neg_lo:[1,0,0] neg_hi:[1,0,0]
	v_pk_fma_f32 v[38:39], v[152:153], v[26:27], v[38:39] op_sel_hi:[0,1,1] neg_lo:[1,0,0] neg_hi:[1,0,0]
	v_pk_fma_f32 v[36:37], v[152:153], v[24:25], v[36:37] op_sel_hi:[0,1,1] neg_lo:[1,0,0] neg_hi:[1,0,0]
	v_pk_fma_f32 v[30:31], v[156:157], v[26:27], v[30:31] op_sel_hi:[0,1,1] neg_lo:[1,0,0] neg_hi:[1,0,0]
	v_pk_fma_f32 v[28:29], v[156:157], v[24:25], v[28:29] op_sel_hi:[0,1,1] neg_lo:[1,0,0] neg_hi:[1,0,0]
	v_pk_fma_f32 v[22:23], v[160:161], v[26:27], v[22:23] op_sel_hi:[0,1,1] neg_lo:[1,0,0] neg_hi:[1,0,0]
	v_pk_fma_f32 v[20:21], v[160:161], v[24:25], v[20:21] op_sel_hi:[0,1,1] neg_lo:[1,0,0] neg_hi:[1,0,0]
	v_pk_fma_f32 v[18:19], v[164:165], v[26:27], v[18:19] op_sel_hi:[0,1,1] neg_lo:[1,0,0] neg_hi:[1,0,0]
	v_pk_fma_f32 v[16:17], v[164:165], v[24:25], v[16:17] op_sel_hi:[0,1,1] neg_lo:[1,0,0] neg_hi:[1,0,0]
	v_pk_fma_f32 v[14:15], v[180:181], v[26:27], v[14:15] op_sel_hi:[0,1,1] neg_lo:[1,0,0] neg_hi:[1,0,0]
	v_pk_fma_f32 v[12:13], v[180:181], v[24:25], v[12:13] op_sel_hi:[0,1,1] neg_lo:[1,0,0] neg_hi:[1,0,0]
	v_pk_fma_f32 v[10:11], v[184:185], v[26:27], v[10:11] op_sel_hi:[0,1,1] neg_lo:[1,0,0] neg_hi:[1,0,0]
	v_pk_fma_f32 v[8:9], v[184:185], v[24:25], v[8:9] op_sel_hi:[0,1,1] neg_lo:[1,0,0] neg_hi:[1,0,0]
	v_pk_fma_f32 v[6:7], v[188:189], v[26:27], v[6:7] op_sel_hi:[0,1,1] neg_lo:[1,0,0] neg_hi:[1,0,0]
	v_pk_fma_f32 v[4:5], v[188:189], v[24:25], v[4:5] op_sel_hi:[0,1,1] neg_lo:[1,0,0] neg_hi:[1,0,0]
	s_waitcnt lgkmcnt(0)
	v_pk_fma_f32 v[42:43], v[150:151], v[42:43], v[32:33] op_sel_hi:[0,1,1]
	v_pk_fma_f32 v[40:41], v[150:151], v[40:41], v[34:35] op_sel_hi:[0,1,1]
	v_pk_fma_f32 v[36:37], v[154:155], v[36:37], v[32:33] op_sel_hi:[0,1,1]
	v_pk_fma_f32 v[38:39], v[154:155], v[38:39], v[34:35] op_sel_hi:[0,1,1]
	v_pk_fma_f32 v[28:29], v[158:159], v[28:29], v[32:33] op_sel_hi:[0,1,1]
	v_pk_fma_f32 v[30:31], v[158:159], v[30:31], v[34:35] op_sel_hi:[0,1,1]
	v_pk_fma_f32 v[20:21], v[162:163], v[20:21], v[32:33] op_sel_hi:[0,1,1]
	v_pk_fma_f32 v[22:23], v[162:163], v[22:23], v[34:35] op_sel_hi:[0,1,1]
	v_pk_fma_f32 v[16:17], v[166:167], v[16:17], v[32:33] op_sel_hi:[0,1,1]
	v_pk_fma_f32 v[18:19], v[166:167], v[18:19], v[34:35] op_sel_hi:[0,1,1]
	v_pk_fma_f32 v[12:13], v[182:183], v[12:13], v[32:33] op_sel_hi:[0,1,1]
	v_pk_fma_f32 v[14:15], v[182:183], v[14:15], v[34:35] op_sel_hi:[0,1,1]
	v_pk_fma_f32 v[8:9], v[186:187], v[8:9], v[32:33] op_sel_hi:[0,1,1]
	v_pk_fma_f32 v[10:11], v[186:187], v[10:11], v[34:35] op_sel_hi:[0,1,1]
	v_pk_fma_f32 v[4:5], v[190:191], v[4:5], v[32:33] op_sel_hi:[0,1,1]
	v_pk_fma_f32 v[6:7], v[190:191], v[6:7], v[34:35] op_sel_hi:[0,1,1]
	v_pk_mul_f32 v[40:41], v[40:41], s[84:85] op_sel_hi:[1,0]
	v_pk_mul_f32 v[42:43], v[42:43], s[84:85] op_sel_hi:[1,0]
	v_pk_mul_f32 v[38:39], v[38:39], s[84:85] op_sel_hi:[1,0]
	v_pk_mul_f32 v[36:37], v[36:37], s[84:85] op_sel_hi:[1,0]
	v_pk_mul_f32 v[30:31], v[30:31], s[84:85] op_sel_hi:[1,0]
	v_pk_mul_f32 v[28:29], v[28:29], s[84:85] op_sel_hi:[1,0]
	v_pk_mul_f32 v[22:23], v[22:23], s[84:85] op_sel_hi:[1,0]
	v_pk_mul_f32 v[20:21], v[20:21], s[84:85] op_sel_hi:[1,0]
	v_pk_mul_f32 v[18:19], v[18:19], s[84:85] op_sel_hi:[1,0]
	v_pk_mul_f32 v[16:17], v[16:17], s[84:85] op_sel_hi:[1,0]
	v_pk_mul_f32 v[14:15], v[14:15], s[84:85] op_sel_hi:[1,0]
	v_pk_mul_f32 v[12:13], v[12:13], s[84:85] op_sel_hi:[1,0]
	v_pk_mul_f32 v[10:11], v[10:11], s[84:85] op_sel_hi:[1,0]
	v_pk_mul_f32 v[8:9], v[8:9], s[84:85] op_sel_hi:[1,0]
	v_pk_mul_f32 v[6:7], v[6:7], s[84:85] op_sel_hi:[1,0]
	v_pk_mul_f32 v[4:5], v[4:5], s[84:85] op_sel_hi:[1,0]
	v_cvt_pk_bf16_f32 v42, v42, v43
	v_cvt_pk_bf16_f32 v43, v40, v41
	v_cvt_pk_bf16_f32 v36, v36, v37
	v_cvt_pk_bf16_f32 v37, v38, v39
	v_cvt_pk_bf16_f32 v28, v28, v29
	v_cvt_pk_bf16_f32 v29, v30, v31
	v_cvt_pk_bf16_f32 v20, v20, v21
	v_cvt_pk_bf16_f32 v21, v22, v23
	v_cvt_pk_bf16_f32 v16, v16, v17
	v_cvt_pk_bf16_f32 v17, v18, v19
	v_cvt_pk_bf16_f32 v12, v12, v13
	v_cvt_pk_bf16_f32 v13, v14, v15
	v_cvt_pk_bf16_f32 v8, v8, v9
	v_cvt_pk_bf16_f32 v9, v10, v11
	v_cvt_pk_bf16_f32 v4, v4, v5
	v_cvt_pk_bf16_f32 v5, v6, v7
	global_store_dwordx2 v[128:129], v[42:43], off offset:288
	global_store_dwordx2 v[124:125], v[36:37], off offset:288
	global_store_dwordx2 v[120:121], v[28:29], off offset:288
	global_store_dwordx2 v[116:117], v[20:21], off offset:288
	global_store_dwordx2 v[112:113], v[16:17], off offset:288
	global_store_dwordx2 v[104:105], v[12:13], off offset:288
	global_store_dwordx2 v[96:97], v[8:9], off offset:288
	global_store_dwordx2 v[88:89], v[4:5], off offset:288
	s_cbranch_vccnz .LBB0_2015
	s_and_b64 vcc, exec, s[38:39]
	s_cbranch_vccnz .LBB0_2014
	s_barrier
	s_branch .LBB0_2014

;     __device__ __forceinline__ void operator()(int row, int col, f32x4 v, int, float&, float&) const { *(u32x2*)(O + (size_t)row * ldc + col) = pk4(v * s); }
; __device__ __forceinline__ void stats_main(const float* stm, int row, int fq, float& mu, float& rs) {
;     const f32x4* p = (const f32x4*)(stm + (size_t)row * 32 + fq * 8);
;     const f32x4 a = p[0], b = p[1];
;     float s1 = (a.x + a.z) + (b.x + b.z), s2 = (a.y + a.w) + (b.y + b.w);
;     s1 += __shfl_xor(s1, 16); s2 += __shfl_xor(s2, 16); s1 += __shfl_xor(s1, 32); s2 += __shfl_xor(s2, 32);
;     mu = s1 * (1.f / DM); rs = __builtin_amdgcn_rsqf(fmaxf(s2 * (1.f / DM) - mu * mu, 0.f) + LN_EPS);
; }
;     __device__ __forceinline__ void operator()(const f32x4 (&acc)[2][2][4][2], const pg8::Unit& u, int wr, int wc, int fr, int fq) const {
;         float mu[2][4], rs[2][4], ps1[2][4], ps2[2][4];
; #pragma unroll
;         for (int ai = 0; ai < 2; ++ai)
; #pragma unroll
;             for (int m = 0; m < 4; ++m) { ps1[ai][m] = 0.f; ps2[ai][m] = 0.f; mu[ai][m] = 0.f; rs[ai][m] = 1.f; if (fold) stats_main(stm, u.pm * 256 + ai * 128 + wr * 64 + m * 16 + fr, fq, mu[ai][m], rs[ai][m]); }
; #pragma unroll
;         for (int bj = 0; bj < 2; ++bj)
; #pragma unroll
;             for (int n = 0; n < 2; ++n) {
;                 const int col = u.pn * 256 + bj * 128 + wc * 32 + n * 16 + fq * 4;
;                 f32x4 c1v = (f32x4){0.f, 0.f, 0.f, 0.f}, c2v = c1v;
;                 if (fold) { c1v = *(const f32x4*)(c1 + col); c2v = *(const f32x4*)(c2 + col); }
.LBB0_2299:
	v_and_b32_e32 v238, 0xfffffff0, v155
	v_lshl_add_u32 v238, s22, 8, v238
	v_and_b32_e32 v239, 31, v219
	v_add_u32_e32 v238, v238, v239
	v_lshrrev_b32_e32 v239, 5, v219
	v_lshl_add_u32 v238, v239, 7, v238
	v_lshlrev_b32_e32 v238, 2, v238
	global_load_dword v242, v238, s[42:43]
	global_load_dword v243, v238, s[46:47]
	v_lshl_add_u32 v238, s23, 8, v3
	v_lshlrev_b32_e32 v246, 7, v238
	v_mov_b32_e32 v247, 0
	v_lshlrev_b32_e32 v248, 7, v238
	v_mov_b32_e32 v249, 0
	v_add_u32_e32 v246, 0x1000, v246
	v_add_u32_e32 v248, 0x5000, v248
	v_lshl_add_u64 v[246:247], v[246:247], 0, v[142:143]
	v_lshl_add_u64 v[248:249], v[248:249], 0, v[142:143]
	global_load_dwordx4 v[214:217], v[246:247], off offset:-4080
	global_load_dwordx4 v[234:237], v[246:247], off offset:-4096
	v_lshrrev_b32_e32 v238, 6, v3
	v_lshrrev_b32_e32 v239, 5, v155
	v_lshl_add_u32 v238, v238, 2, v239
	v_lshlrev_b32_e32 v238, 9, v238
	v_and_b32_e32 v239, 12, v155
	v_lshl_add_u32 v255, v239, 2, v238
	v_add_u32_e32 v255, 0x20000, v255
	v_lshl_add_u32 v238, v219, 2, v238
	v_add_u32_e32 v238, 0x20000, v238
	s_waitcnt vmcnt(3)
	ds_write_b32 v238, v242
	s_waitcnt vmcnt(2)
	ds_write_b32 v238, v243 offset:256
	global_load_dwordx4 v[238:241], v[246:247], off offset:-2032
	global_load_dwordx4 v[242:245], v[246:247], off offset:-2048
	s_waitcnt lgkmcnt(0)
	v_lshl_add_u32 v192, s23, 8, v3
	v_ashrrev_i32_e32 v193, 31, v192
	v_lshlrev_b64 v[132:133], 7, v[192:193]
	v_lshl_add_u64 v[136:137], v[142:143], 0, v[132:133]
	s_waitcnt vmcnt(3)
	v_mov_b64_e32 v[132:133], v[214:215]
	v_mov_b64_e32 v[134:135], v[216:217]
	global_load_dwordx4 v[214:217], v[246:247], off offset:16
	s_nop 0
	s_waitcnt vmcnt(3)
	v_mov_b64_e32 v[136:137], v[234:235]
	v_mov_b64_e32 v[138:139], v[236:237]
	global_load_dwordx4 v[234:237], v[246:247], off
	v_and_b32_e32 v149, 64, v219
	v_xor_b32_e32 v148, 16, v219
	v_add_u32_e32 v149, 64, v149
	v_cmp_lt_i32_e32 vcc, v148, v149
	v_or_b32_e32 v194, 16, v192
	v_ashrrev_i32_e32 v195, 31, v194
	v_cndmask_b32_e32 v148, v219, v148, vcc
	v_lshlrev_b32_e32 v160, 2, v148
	v_xor_b32_e32 v148, 32, v219
	v_cmp_lt_i32_e32 vcc, v148, v149
	v_or_b32_e32 v196, 32, v192
	v_ashrrev_i32_e32 v197, 31, v196
	v_cndmask_b32_e32 v148, v219, v148, vcc
	v_lshlrev_b32_e32 v161, 2, v148
	v_or_b32_e32 v204, 48, v192
	v_ashrrev_i32_e32 v205, 31, v204
	v_add_u32_e32 v206, 0x80, v192
	v_ashrrev_i32_e32 v207, 31, v206
	v_add_u32_e32 v202, 0x90, v192
	v_ashrrev_i32_e32 v203, 31, v202
	v_add_u32_e32 v200, 0xa0, v192
	v_ashrrev_i32_e32 v201, 31, v200
	v_add_u32_e32 v198, 0xb0, v192
	v_ashrrev_i32_e32 v199, 31, v198
	v_lshl_add_u32 v208, s22, 8, v155
	v_ashrrev_i32_e32 v209, 31, v208
	v_readlane_b32 s0, v254, 42
	v_readlane_b32 s1, v254, 43
	v_readlane_b32 s24, v251, 0
	s_andn2_b64 vcc, exec, s[40:41]
	v_readlane_b32 s25, v251, 1
	v_readlane_b32 s26, v251, 2
	v_readlane_b32 s27, v251, 3
	s_waitcnt lgkmcnt(0)
	v_pk_add_f32 v[132:133], v[132:133], v[134:135]
	v_pk_add_f32 v[136:137], v[136:137], v[138:139]
	s_nop 0
	v_pk_add_f32 v[132:133], v[136:137], v[132:133]
	ds_bpermute_b32 v134, v160, v132
	ds_bpermute_b32 v135, v160, v133
	s_waitcnt lgkmcnt(0)
	v_pk_add_f32 v[132:133], v[132:133], v[134:135]
	ds_bpermute_b32 v134, v161, v132
	ds_bpermute_b32 v135, v161, v133
	s_waitcnt lgkmcnt(0)
	v_pk_add_f32 v[132:133], v[132:133], v[134:135]
	s_nop 0
	v_pk_mul_f32 v[148:149], v[132:133], s[82:83] op_sel_hi:[1,0]
	s_nop 0
	v_fma_f32 v132, -v148, v148, v149
	v_max_f32_e32 v132, 0, v132
	v_add_f32_e32 v132, 0x3727c5ac, v132
	v_rsq_f32_e32 v150, v132
	v_lshlrev_b64 v[132:133], 7, v[194:195]
	v_lshl_add_u64 v[136:137], v[142:143], 0, v[132:133]
	s_waitcnt vmcnt(3)
	v_mov_b64_e32 v[132:133], v[238:239]
	v_mov_b64_e32 v[134:135], v[240:241]
	global_load_dwordx4 v[238:241], v[246:247], off offset:2064
	s_nop 0
	s_waitcnt vmcnt(3)
	v_mov_b64_e32 v[136:137], v[242:243]
	v_mov_b64_e32 v[138:139], v[244:245]
	global_load_dwordx4 v[242:245], v[246:247], off offset:2048
	s_waitcnt lgkmcnt(0)
	v_pk_add_f32 v[132:133], v[132:133], v[134:135]
	s_waitcnt lgkmcnt(0)
	v_pk_add_f32 v[136:137], v[136:137], v[138:139]
	s_nop 0
	v_pk_add_f32 v[132:133], v[136:137], v[132:133]
	ds_bpermute_b32 v134, v160, v132
	ds_bpermute_b32 v135, v160, v133
	s_waitcnt lgkmcnt(0)
	v_pk_add_f32 v[132:133], v[132:133], v[134:135]
	ds_bpermute_b32 v134, v161, v132
	ds_bpermute_b32 v135, v161, v133
	s_waitcnt lgkmcnt(0)
	v_pk_add_f32 v[132:133], v[132:133], v[134:135]
	s_nop 0
	v_pk_mul_f32 v[152:153], v[132:133], s[82:83] op_sel_hi:[1,0]
	s_nop 0
	v_fma_f32 v132, -v152, v152, v153
	v_max_f32_e32 v132, 0, v132
	v_add_f32_e32 v132, 0x3727c5ac, v132
	v_rsq_f32_e32 v154, v132
	v_lshlrev_b64 v[132:133], 7, v[196:197]
	v_lshl_add_u64 v[136:137], v[142:143], 0, v[132:133]
	s_waitcnt vmcnt(3)
	v_mov_b64_e32 v[132:133], v[214:215]
	v_mov_b64_e32 v[134:135], v[216:217]
	global_load_dwordx4 v[214:217], v[248:249], off offset:-4080
	s_nop 0
	s_waitcnt vmcnt(3)
	v_mov_b64_e32 v[136:137], v[234:235]
	v_mov_b64_e32 v[138:139], v[236:237]
	global_load_dwordx4 v[234:237], v[248:249], off offset:-4096
	s_waitcnt lgkmcnt(0)
	v_pk_add_f32 v[132:133], v[132:133], v[134:135]
	s_waitcnt lgkmcnt(0)
	v_pk_add_f32 v[136:137], v[136:137], v[138:139]
	s_nop 0
	v_pk_add_f32 v[132:133], v[136:137], v[132:133]
	ds_bpermute_b32 v134, v160, v132
	ds_bpermute_b32 v135, v160, v133
	s_waitcnt lgkmcnt(0)
	v_pk_add_f32 v[132:133], v[132:133], v[134:135]
	ds_bpermute_b32 v134, v161, v132
	ds_bpermute_b32 v135, v161, v133
	s_waitcnt lgkmcnt(0)
; __device__ __forceinline__ void stats_main(const float* stm, int row, int fq, float& mu, float& rs) {
;     const f32x4* p = (const f32x4*)(stm + (size_t)row * 32 + fq * 8);
;     const f32x4 a = p[0], b = p[1];
;     float s1 = (a.x + a.z) + (b.x + b.z), s2 = (a.y + a.w) + (b.y + b.w);
;     s1 += __shfl_xor(s1, 16); s2 += __shfl_xor(s2, 16); s1 += __shfl_xor(s1, 32); s2 += __shfl_xor(s2, 32);
;     mu = s1 * (1.f / DM); rs = __builtin_amdgcn_rsqf(fmaxf(s2 * (1.f / DM) - mu * mu, 0.f) + LN_EPS);
; }
;     __device__ __forceinline__ void operator()(const f32x4 (&acc)[2][2][4][2], const pg8::Unit& u, int wr, int wc, int fr, int fq) const {
;     ...
;             for (int m = 0; m < 4; ++m) { ps1[ai][m] = 0.f; ps2[ai][m] = 0.f; mu[ai][m] = 0.f; rs[ai][m] = 1.f; if (fold) stats_main(stm, u.pm * 256 + ai * 128 + wr * 64 + m * 16 + fr, fq, mu[ai][m], rs[ai][m]); }
; #pragma unroll
;         for (int bj = 0; bj < 2; ++bj)
; #pragma unroll
;             for (int n = 0; n < 2; ++n) {
;                 const int col = u.pn * 256 + bj * 128 + wc * 32 + n * 16 + fq * 4;
;                 f32x4 c1v = (f32x4){0.f, 0.f, 0.f, 0.f}, c2v = c1v;
;                 if (fold) { c1v = *(const f32x4*)(c1 + col); c2v = *(const f32x4*)(c2 + col); }
	v_pk_add_f32 v[132:133], v[132:133], v[134:135]
	s_nop 0
	v_pk_mul_f32 v[156:157], v[132:133], s[82:83] op_sel_hi:[1,0]
	s_nop 0
	v_fma_f32 v132, -v156, v156, v157
	v_max_f32_e32 v132, 0, v132
	v_add_f32_e32 v132, 0x3727c5ac, v132
	v_rsq_f32_e32 v158, v132
	v_lshlrev_b64 v[132:133], 7, v[204:205]
	v_lshl_add_u64 v[136:137], v[142:143], 0, v[132:133]
	s_waitcnt vmcnt(3)
	v_mov_b64_e32 v[132:133], v[238:239]
	v_mov_b64_e32 v[134:135], v[240:241]
	global_load_dwordx4 v[238:241], v[248:249], off offset:-2032
	s_nop 0
	s_waitcnt vmcnt(3)
	v_mov_b64_e32 v[136:137], v[242:243]
	v_mov_b64_e32 v[138:139], v[244:245]
	global_load_dwordx4 v[242:245], v[248:249], off offset:-2048
	s_waitcnt lgkmcnt(0)
	v_pk_add_f32 v[132:133], v[132:133], v[134:135]
	s_waitcnt lgkmcnt(0)
	v_pk_add_f32 v[136:137], v[136:137], v[138:139]
	s_nop 0
	v_pk_add_f32 v[132:133], v[136:137], v[132:133]
	ds_bpermute_b32 v134, v160, v132
	ds_bpermute_b32 v135, v160, v133
	s_waitcnt lgkmcnt(0)
	v_pk_add_f32 v[132:133], v[132:133], v[134:135]
	ds_bpermute_b32 v134, v161, v132
	ds_bpermute_b32 v135, v161, v133
	s_waitcnt lgkmcnt(0)
	v_pk_add_f32 v[132:133], v[132:133], v[134:135]
	s_nop 0
	v_pk_mul_f32 v[184:185], v[132:133], s[82:83] op_sel_hi:[1,0]
	s_nop 0
	v_fma_f32 v132, -v184, v184, v185
	v_max_f32_e32 v132, 0, v132
	v_add_f32_e32 v132, 0x3727c5ac, v132
	v_rsq_f32_e32 v190, v132
	v_lshlrev_b64 v[132:133], 7, v[206:207]
	v_lshl_add_u64 v[136:137], v[142:143], 0, v[132:133]
	s_waitcnt vmcnt(3)
	v_mov_b64_e32 v[132:133], v[214:215]
	v_mov_b64_e32 v[134:135], v[216:217]
	global_load_dwordx4 v[214:217], v[248:249], off offset:16
	s_nop 0
	s_waitcnt vmcnt(3)
	v_mov_b64_e32 v[136:137], v[234:235]
	v_mov_b64_e32 v[138:139], v[236:237]
	global_load_dwordx4 v[234:237], v[248:249], off
	s_waitcnt lgkmcnt(0)
	v_pk_add_f32 v[132:133], v[132:133], v[134:135]
	s_waitcnt lgkmcnt(0)
	v_pk_add_f32 v[136:137], v[136:137], v[138:139]
	s_nop 0
	v_pk_add_f32 v[132:133], v[136:137], v[132:133]
	ds_bpermute_b32 v134, v160, v132
	ds_bpermute_b32 v135, v160, v133
	s_waitcnt lgkmcnt(0)
	v_pk_add_f32 v[132:133], v[132:133], v[134:135]
	ds_bpermute_b32 v134, v161, v132
	ds_bpermute_b32 v135, v161, v133
	s_waitcnt lgkmcnt(0)
	v_pk_add_f32 v[132:133], v[132:133], v[134:135]
	s_nop 0
	v_pk_mul_f32 v[180:181], v[132:133], s[82:83] op_sel_hi:[1,0]
	s_nop 0
	v_fma_f32 v132, -v180, v180, v181
	v_max_f32_e32 v132, 0, v132
	v_add_f32_e32 v132, 0x3727c5ac, v132
	v_rsq_f32_e32 v188, v132
	v_lshlrev_b64 v[132:133], 7, v[202:203]
	v_lshl_add_u64 v[136:137], v[142:143], 0, v[132:133]
	s_waitcnt vmcnt(3)
	v_mov_b64_e32 v[132:133], v[238:239]
	v_mov_b64_e32 v[134:135], v[240:241]
	global_load_dwordx4 v[238:241], v[248:249], off offset:2064
	s_nop 0
	s_waitcnt vmcnt(3)
	v_mov_b64_e32 v[136:137], v[242:243]
	v_mov_b64_e32 v[138:139], v[244:245]
	global_load_dwordx4 v[242:245], v[248:249], off offset:2048
	s_waitcnt lgkmcnt(0)
	v_pk_add_f32 v[132:133], v[132:133], v[134:135]
	s_waitcnt lgkmcnt(0)
	v_pk_add_f32 v[136:137], v[136:137], v[138:139]
	s_nop 0
	v_pk_add_f32 v[132:133], v[136:137], v[132:133]
	ds_bpermute_b32 v134, v160, v132
	ds_bpermute_b32 v135, v160, v133
	s_waitcnt lgkmcnt(0)
	v_pk_add_f32 v[132:133], v[132:133], v[134:135]
	ds_bpermute_b32 v134, v161, v132
	ds_bpermute_b32 v135, v161, v133
	s_waitcnt lgkmcnt(0)
	v_pk_add_f32 v[132:133], v[132:133], v[134:135]
	s_nop 0
	v_pk_mul_f32 v[164:165], v[132:133], s[82:83] op_sel_hi:[1,0]
	s_nop 0
	v_fma_f32 v132, -v164, v164, v165
	v_max_f32_e32 v132, 0, v132
	v_add_f32_e32 v132, 0x3727c5ac, v132
	v_rsq_f32_e32 v186, v132
	v_lshlrev_b64 v[132:133], 7, v[200:201]
	v_lshl_add_u64 v[136:137], v[142:143], 0, v[132:133]
	s_waitcnt vmcnt(3)
	v_mov_b64_e32 v[132:133], v[214:215]
	v_mov_b64_e32 v[134:135], v[216:217]
	s_nop 0
	s_waitcnt vmcnt(2)
	v_mov_b64_e32 v[136:137], v[234:235]
	v_mov_b64_e32 v[138:139], v[236:237]
	s_waitcnt lgkmcnt(0)
	v_pk_add_f32 v[132:133], v[132:133], v[134:135]
	s_waitcnt lgkmcnt(0)
	v_pk_add_f32 v[136:137], v[136:137], v[138:139]
	s_nop 0
	v_pk_add_f32 v[132:133], v[136:137], v[132:133]
	ds_bpermute_b32 v134, v160, v132
	ds_bpermute_b32 v135, v160, v133
	s_waitcnt lgkmcnt(0)
	v_pk_add_f32 v[132:133], v[132:133], v[134:135]
	ds_bpermute_b32 v134, v161, v132
	ds_bpermute_b32 v135, v161, v133
	s_waitcnt lgkmcnt(0)
	v_pk_add_f32 v[132:133], v[132:133], v[134:135]
	s_nop 0
	v_pk_mul_f32 v[162:163], v[132:133], s[82:83] op_sel_hi:[1,0]
	s_nop 0
	v_fma_f32 v132, -v162, v162, v163
	v_max_f32_e32 v132, 0, v132
	v_add_f32_e32 v132, 0x3727c5ac, v132
	v_rsq_f32_e32 v182, v132
	v_lshlrev_b64 v[132:133], 7, v[198:199]
	v_lshl_add_u64 v[136:137], v[142:143], 0, v[132:133]
	s_waitcnt vmcnt(1)
	v_mov_b64_e32 v[132:133], v[238:239]
	v_mov_b64_e32 v[134:135], v[240:241]
	s_nop 0
	s_waitcnt vmcnt(0)
	v_mov_b64_e32 v[136:137], v[242:243]
	v_mov_b64_e32 v[138:139], v[244:245]
	s_waitcnt lgkmcnt(0)
	v_pk_add_f32 v[132:133], v[132:133], v[134:135]
	s_waitcnt lgkmcnt(0)
	v_pk_add_f32 v[136:137], v[136:137], v[138:139]
	s_nop 0
	v_pk_add_f32 v[132:133], v[136:137], v[132:133]
	ds_bpermute_b32 v134, v160, v132
	ds_bpermute_b32 v135, v160, v133
	v_lshlrev_b64 v[136:137], 2, v[208:209]
	s_waitcnt lgkmcnt(0)
	v_pk_add_f32 v[132:133], v[132:133], v[134:135]
	ds_bpermute_b32 v134, v161, v132
	ds_bpermute_b32 v135, v161, v133
	s_waitcnt lgkmcnt(0)
	v_pk_add_f32 v[132:133], v[132:133], v[134:135]
	s_nop 0
	v_pk_mul_f32 v[160:161], v[132:133], s[82:83] op_sel_hi:[1,0]
	s_nop 0
	v_fma_f32 v132, -v160, v160, v161
	v_max_f32_e32 v132, 0, v132
	v_add_f32_e32 v132, 0x3727c5ac, v132
	v_rsq_f32_e32 v166, v132
	v_lshl_add_u64 v[132:133], s[42:43], 0, v[136:137]
	ds_read_b128 v[132:135], v255
	v_lshl_add_u64 v[136:137], s[46:47], 0, v[136:137]
	ds_read_b128 v[136:139], v255 offset:256
	s_waitcnt lgkmcnt(0)
; __device__ __forceinline__ u32x2 pk4(f32x4 v) { u32x2 r; r.x = pk2(v.x, v.y); r.y = pk2(v.z, v.w); return r; }
;     __device__ __forceinline__ void operator()(int row, int col, f32x4 v, int, float&, float&) const { *(u32x2*)(O + (size_t)row * ldc + col) = pk4(v * s); }
;     __device__ __forceinline__ void operator()(const f32x4 (&acc)[2][2][4][2], const pg8::Unit& u, int wr, int wc, int fr, int fq) const {
;     ...
; #pragma unroll
;                 for (int ai = 0; ai < 2; ++ai)
; #pragma unroll
;                     for (int m = 0; m < 4; ++m) {
;                         f32x4 v = acc[ai][bj][m][n];
;                         if (fold) v = (v - c1v * mu[ai][m]) * rs[ai][m] + c2v;
;                         f(u.pm * 256 + ai * 128 + wr * 64 + m * 16 + fr, col, v, fq, ps1[ai][m], ps2[ai][m]);
;                     }
;     __device__ __forceinline__ void operator()(int row, int col, f32x4 v, int, float&, float&) const {
;         f32x4 r; r.x = fmaxf(v.x, 0.f); r.y = fmaxf(v.y, 0.f); r.z = fmaxf(v.z, 0.f); r.w = fmaxf(v.w, 0.f);
;         *(u32x2*)(O + (size_t)row * FF + col) = pk4(r * r);
;     }
	v_pk_fma_f32 v[128:129], v[148:149], v[132:133], v[128:129] op_sel_hi:[0,1,1] neg_lo:[1,0,0] neg_hi:[1,0,0]
	v_pk_fma_f32 v[130:131], v[148:149], v[134:135], v[130:131] op_sel_hi:[0,1,1] neg_lo:[1,0,0] neg_hi:[1,0,0]
	s_waitcnt lgkmcnt(0)
	v_pk_fma_f32 v[128:129], v[150:151], v[128:129], v[136:137] op_sel_hi:[0,1,1]
	v_pk_fma_f32 v[130:131], v[150:151], v[130:131], v[138:139] op_sel_hi:[0,1,1]
	v_max_f32_e32 v128, 0, v128
	v_max_f32_e32 v129, 0, v129
	v_max_f32_e32 v130, 0, v130
	v_max_f32_e32 v131, 0, v131
	v_pk_mul_f32 v[128:129], v[128:129], v[128:129]
	v_pk_fma_f32 v[126:127], v[152:153], v[134:135], v[126:127] op_sel_hi:[0,1,1] neg_lo:[1,0,0] neg_hi:[1,0,0]
	v_pk_fma_f32 v[122:123], v[156:157], v[134:135], v[122:123] op_sel_hi:[0,1,1] neg_lo:[1,0,0] neg_hi:[1,0,0]
	v_pk_fma_f32 v[118:119], v[184:185], v[134:135], v[118:119] op_sel_hi:[0,1,1] neg_lo:[1,0,0] neg_hi:[1,0,0]
	v_pk_fma_f32 v[114:115], v[180:181], v[134:135], v[114:115] op_sel_hi:[0,1,1] neg_lo:[1,0,0] neg_hi:[1,0,0]
	v_pk_fma_f32 v[110:111], v[164:165], v[134:135], v[110:111] op_sel_hi:[0,1,1] neg_lo:[1,0,0] neg_hi:[1,0,0]
	v_pk_fma_f32 v[102:103], v[162:163], v[134:135], v[102:103] op_sel_hi:[0,1,1] neg_lo:[1,0,0] neg_hi:[1,0,0]
	v_pk_mul_f32 v[130:131], v[130:131], v[130:131]
	v_cvt_pk_bf16_f32 v168, v128, v129
	v_lshlrev_b64 v[128:129], 13, v[192:193]
	v_pk_fma_f32 v[126:127], v[154:155], v[126:127], v[138:139] op_sel_hi:[0,1,1]
	v_pk_fma_f32 v[122:123], v[158:159], v[122:123], v[138:139] op_sel_hi:[0,1,1]
	v_pk_fma_f32 v[118:119], v[190:191], v[118:119], v[138:139] op_sel_hi:[0,1,1]
	v_pk_fma_f32 v[114:115], v[188:189], v[114:115], v[138:139] op_sel_hi:[0,1,1]
	v_pk_fma_f32 v[110:111], v[186:187], v[110:111], v[138:139] op_sel_hi:[0,1,1]
	v_pk_fma_f32 v[102:103], v[182:183], v[102:103], v[138:139] op_sel_hi:[0,1,1]
	v_cvt_pk_bf16_f32 v169, v130, v131
	v_lshl_add_u64 v[128:129], s[0:1], 0, v[128:129]
	v_lshlrev_b64 v[130:131], 1, v[208:209]
	v_max_f32_e32 v126, 0, v126
	v_max_f32_e32 v127, 0, v127
	v_max_f32_e32 v122, 0, v122
	v_max_f32_e32 v123, 0, v123
	v_max_f32_e32 v118, 0, v118
	v_max_f32_e32 v119, 0, v119
	v_max_f32_e32 v114, 0, v114
	v_max_f32_e32 v115, 0, v115
	v_max_f32_e32 v110, 0, v110
	v_max_f32_e32 v111, 0, v111
	v_max_f32_e32 v102, 0, v102
	v_max_f32_e32 v103, 0, v103
	v_lshl_add_u64 v[128:129], v[128:129], 0, v[130:131]
	v_pk_mul_f32 v[126:127], v[126:127], v[126:127]
	v_pk_mul_f32 v[122:123], v[122:123], v[122:123]
	v_pk_mul_f32 v[118:119], v[118:119], v[118:119]
	v_pk_mul_f32 v[114:115], v[114:115], v[114:115]
	v_pk_mul_f32 v[110:111], v[110:111], v[110:111]
	v_pk_mul_f32 v[102:103], v[102:103], v[102:103]
	global_store_dwordx2 v[128:129], v[168:169], off
	v_cvt_pk_bf16_f32 v169, v126, v127
	v_cvt_pk_bf16_f32 v127, v122, v123
	v_cvt_pk_bf16_f32 v123, v118, v119
	v_cvt_pk_bf16_f32 v119, v114, v115
	v_cvt_pk_bf16_f32 v115, v110, v111
	v_cvt_pk_bf16_f32 v111, v102, v103
	v_xor_b32_e32 v103, 0x80000000, v135
	v_xor_b32_e32 v102, 0x80000000, v134
	v_pk_fma_f32 v[124:125], v[152:153], v[132:133], v[124:125] op_sel_hi:[0,1,1] neg_lo:[1,0,0] neg_hi:[1,0,0]
	v_pk_fma_f32 v[120:121], v[156:157], v[132:133], v[120:121] op_sel_hi:[0,1,1] neg_lo:[1,0,0] neg_hi:[1,0,0]
	v_pk_fma_f32 v[116:117], v[184:185], v[132:133], v[116:117] op_sel_hi:[0,1,1] neg_lo:[1,0,0] neg_hi:[1,0,0]
	v_pk_fma_f32 v[112:113], v[180:181], v[132:133], v[112:113] op_sel_hi:[0,1,1] neg_lo:[1,0,0] neg_hi:[1,0,0]
	v_pk_fma_f32 v[108:109], v[164:165], v[132:133], v[108:109] op_sel_hi:[0,1,1] neg_lo:[1,0,0] neg_hi:[1,0,0]
	v_pk_fma_f32 v[100:101], v[162:163], v[132:133], v[100:101] op_sel_hi:[0,1,1] neg_lo:[1,0,0] neg_hi:[1,0,0]
	v_pk_fma_f32 v[92:93], v[132:133], v[160:161], v[92:93] op_sel_hi:[1,0,1] neg_lo:[1,0,0] neg_hi:[1,0,0]
	v_pk_fma_f32 v[94:95], v[102:103], v[160:161], v[94:95] op_sel_hi:[1,0,1]
	v_pk_fma_f32 v[124:125], v[154:155], v[124:125], v[136:137] op_sel_hi:[0,1,1]
	v_pk_fma_f32 v[120:121], v[158:159], v[120:121], v[136:137] op_sel_hi:[0,1,1]
	v_pk_fma_f32 v[116:117], v[190:191], v[116:117], v[136:137] op_sel_hi:[0,1,1]
	v_pk_fma_f32 v[112:113], v[188:189], v[112:113], v[136:137] op_sel_hi:[0,1,1]
	v_pk_fma_f32 v[108:109], v[186:187], v[108:109], v[136:137] op_sel_hi:[0,1,1]
	v_pk_fma_f32 v[100:101], v[182:183], v[100:101], v[136:137] op_sel_hi:[0,1,1]
	v_pk_fma_f32 v[94:95], v[94:95], v[166:167], v[138:139] op_sel_hi:[1,0,1]
	v_pk_fma_f32 v[92:93], v[92:93], v[166:167], v[136:137] op_sel_hi:[1,0,1]
	v_max_f32_e32 v124, 0, v124
	v_max_f32_e32 v125, 0, v125
	v_max_f32_e32 v120, 0, v120
	v_max_f32_e32 v121, 0, v121
	v_max_f32_e32 v116, 0, v116
	v_max_f32_e32 v117, 0, v117
	v_max_f32_e32 v112, 0, v112
	v_max_f32_e32 v113, 0, v113
	v_max_f32_e32 v108, 0, v108
	v_max_f32_e32 v109, 0, v109
	v_max_f32_e32 v100, 0, v100
	v_max_f32_e32 v101, 0, v101
	v_max_f32_e32 v92, 0, v92
	v_max_f32_e32 v93, 0, v93
	v_max_f32_e32 v94, 0, v94
	v_max_f32_e32 v95, 0, v95
	v_pk_mul_f32 v[124:125], v[124:125], v[124:125]
	v_pk_mul_f32 v[120:121], v[120:121], v[120:121]
	v_pk_mul_f32 v[116:117], v[116:117], v[116:117]
	v_pk_mul_f32 v[112:113], v[112:113], v[112:113]
	v_pk_mul_f32 v[108:109], v[108:109], v[108:109]
	v_pk_mul_f32 v[100:101], v[100:101], v[100:101]
	v_pk_mul_f32 v[94:95], v[94:95], v[94:95]
	v_pk_mul_f32 v[92:93], v[92:93], v[92:93]
	v_cvt_pk_bf16_f32 v168, v124, v125
	v_lshlrev_b64 v[124:125], 13, v[194:195]
	v_cvt_pk_bf16_f32 v126, v120, v121
	v_lshlrev_b64 v[120:121], 13, v[196:197]
	v_cvt_pk_bf16_f32 v122, v116, v117
	v_lshlrev_b64 v[116:117], 13, v[204:205]
	v_cvt_pk_bf16_f32 v118, v112, v113
	v_lshlrev_b64 v[112:113], 13, v[206:207]
	v_cvt_pk_bf16_f32 v114, v108, v109
; __device__ __forceinline__ u32x2 pk4(f32x4 v) { u32x2 r; r.x = pk2(v.x, v.y); r.y = pk2(v.z, v.w); return r; }
;     __device__ __forceinline__ void operator()(int row, int col, f32x4 v, int, float&, float&) const { *(u32x2*)(O + (size_t)row * ldc + col) = pk4(v * s); }
;     __device__ __forceinline__ void operator()(const f32x4 (&acc)[2][2][4][2], const pg8::Unit& u, int wr, int wc, int fr, int fq) const {
;     ...
; #pragma unroll
;                 for (int ai = 0; ai < 2; ++ai)
; #pragma unroll
;                     for (int m = 0; m < 4; ++m) {
;                         f32x4 v = acc[ai][bj][m][n];
;                         if (fold) v = (v - c1v * mu[ai][m]) * rs[ai][m] + c2v;
;                         f(u.pm * 256 + ai * 128 + wr * 64 + m * 16 + fr, col, v, fq, ps1[ai][m], ps2[ai][m]);
;                     }
;     __device__ __forceinline__ void operator()(int row, int col, f32x4 v, int, float&, float&) const {
;         f32x4 r; r.x = fmaxf(v.x, 0.f); r.y = fmaxf(v.y, 0.f); r.z = fmaxf(v.z, 0.f); r.w = fmaxf(v.w, 0.f);
;         *(u32x2*)(O + (size_t)row * FF + col) = pk4(r * r);
;     }
	v_lshlrev_b64 v[108:109], 13, v[202:203]
	v_cvt_pk_bf16_f32 v110, v100, v101
	v_lshlrev_b64 v[100:101], 13, v[200:201]
	v_cvt_pk_bf16_f32 v102, v92, v93
	v_cvt_pk_bf16_f32 v103, v94, v95
	v_lshlrev_b64 v[92:93], 13, v[198:199]
	v_add_u32_e32 v94, 16, v208
	v_lshl_add_u64 v[124:125], s[0:1], 0, v[124:125]
	v_lshl_add_u64 v[120:121], s[0:1], 0, v[120:121]
	v_lshl_add_u64 v[116:117], s[0:1], 0, v[116:117]
	v_lshl_add_u64 v[112:113], s[0:1], 0, v[112:113]
	v_lshl_add_u64 v[108:109], s[0:1], 0, v[108:109]
	v_lshl_add_u64 v[100:101], s[0:1], 0, v[100:101]
	v_lshl_add_u64 v[92:93], s[0:1], 0, v[92:93]
	v_ashrrev_i32_e32 v95, 31, v94
	v_lshl_add_u64 v[124:125], v[124:125], 0, v[130:131]
	v_lshl_add_u64 v[120:121], v[120:121], 0, v[130:131]
	v_lshl_add_u64 v[116:117], v[116:117], 0, v[130:131]
	v_lshl_add_u64 v[112:113], v[112:113], 0, v[130:131]
	v_lshl_add_u64 v[108:109], v[108:109], 0, v[130:131]
	v_lshl_add_u64 v[100:101], v[100:101], 0, v[130:131]
	v_lshl_add_u64 v[92:93], v[92:93], 0, v[130:131]
	v_lshlrev_b64 v[94:95], 2, v[94:95]
	global_store_dwordx2 v[124:125], v[168:169], off
	global_store_dwordx2 v[120:121], v[126:127], off
	global_store_dwordx2 v[116:117], v[122:123], off
	global_store_dwordx2 v[112:113], v[118:119], off
	global_store_dwordx2 v[108:109], v[114:115], off
	global_store_dwordx2 v[100:101], v[110:111], off
	global_store_dwordx2 v[92:93], v[102:103], off
	v_lshl_add_u64 v[102:103], s[42:43], 0, v[94:95]
	ds_read_b128 v[130:133], v255 offset:64
	v_lshl_add_u64 v[94:95], s[46:47], 0, v[94:95]
	ds_read_b128 v[134:137], v255 offset:320
	s_mov_b64 s[0:1], -1
	s_waitcnt lgkmcnt(0)
	v_pk_fma_f32 v[94:95], v[148:149], v[130:131], v[104:105] op_sel_hi:[0,1,1] neg_lo:[1,0,0] neg_hi:[1,0,0]
	v_pk_fma_f32 v[102:103], v[148:149], v[132:133], v[106:107] op_sel_hi:[0,1,1] neg_lo:[1,0,0] neg_hi:[1,0,0]
	s_waitcnt lgkmcnt(0)
	v_pk_fma_f32 v[102:103], v[150:151], v[102:103], v[136:137] op_sel_hi:[0,1,1]
	v_pk_fma_f32 v[94:95], v[150:151], v[94:95], v[134:135] op_sel_hi:[0,1,1]
	v_max_f32_e32 v94, 0, v94
	v_max_f32_e32 v95, 0, v95
	v_max_f32_e32 v102, 0, v102
	v_max_f32_e32 v103, 0, v103
	v_pk_fma_f32 v[64:65], v[160:161], v[130:131], v[64:65] op_sel_hi:[0,1,1] neg_lo:[1,0,0] neg_hi:[1,0,0]
	v_pk_fma_f32 v[66:67], v[160:161], v[132:133], v[66:67] op_sel_hi:[0,1,1] neg_lo:[1,0,0] neg_hi:[1,0,0]
	v_pk_mul_f32 v[102:103], v[102:103], v[102:103]
	v_pk_mul_f32 v[94:95], v[94:95], v[94:95]
	v_pk_fma_f32 v[66:67], v[166:167], v[66:67], v[136:137] op_sel_hi:[0,1,1]
	v_pk_fma_f32 v[64:65], v[166:167], v[64:65], v[134:135] op_sel_hi:[0,1,1]
	v_cvt_pk_bf16_f32 v94, v94, v95
	v_cvt_pk_bf16_f32 v95, v102, v103
	v_pk_fma_f32 v[72:73], v[162:163], v[130:131], v[72:73] op_sel_hi:[0,1,1] neg_lo:[1,0,0] neg_hi:[1,0,0]
	v_pk_fma_f32 v[74:75], v[162:163], v[132:133], v[74:75] op_sel_hi:[0,1,1] neg_lo:[1,0,0] neg_hi:[1,0,0]
	v_max_f32_e32 v64, 0, v64
	v_max_f32_e32 v65, 0, v65
	v_max_f32_e32 v66, 0, v66
	v_max_f32_e32 v67, 0, v67
	global_store_dwordx2 v[128:129], v[94:95], off offset:32
	v_pk_fma_f32 v[94:95], v[152:153], v[130:131], v[96:97] op_sel_hi:[0,1,1] neg_lo:[1,0,0] neg_hi:[1,0,0]
	v_pk_fma_f32 v[96:97], v[152:153], v[132:133], v[98:99] op_sel_hi:[0,1,1] neg_lo:[1,0,0] neg_hi:[1,0,0]
	v_pk_fma_f32 v[88:89], v[156:157], v[130:131], v[88:89] op_sel_hi:[0,1,1] neg_lo:[1,0,0] neg_hi:[1,0,0]
	v_pk_fma_f32 v[90:91], v[156:157], v[132:133], v[90:91] op_sel_hi:[0,1,1] neg_lo:[1,0,0] neg_hi:[1,0,0]
	v_pk_fma_f32 v[84:85], v[184:185], v[130:131], v[84:85] op_sel_hi:[0,1,1] neg_lo:[1,0,0] neg_hi:[1,0,0]
	v_pk_fma_f32 v[86:87], v[184:185], v[132:133], v[86:87] op_sel_hi:[0,1,1] neg_lo:[1,0,0] neg_hi:[1,0,0]
	v_pk_fma_f32 v[80:81], v[180:181], v[130:131], v[80:81] op_sel_hi:[0,1,1] neg_lo:[1,0,0] neg_hi:[1,0,0]
	v_pk_fma_f32 v[82:83], v[180:181], v[132:133], v[82:83] op_sel_hi:[0,1,1] neg_lo:[1,0,0] neg_hi:[1,0,0]
	v_pk_fma_f32 v[76:77], v[164:165], v[130:131], v[76:77] op_sel_hi:[0,1,1] neg_lo:[1,0,0] neg_hi:[1,0,0]
	v_pk_fma_f32 v[78:79], v[164:165], v[132:133], v[78:79] op_sel_hi:[0,1,1] neg_lo:[1,0,0] neg_hi:[1,0,0]
	v_pk_fma_f32 v[74:75], v[182:183], v[74:75], v[136:137] op_sel_hi:[0,1,1]
	v_pk_fma_f32 v[72:73], v[182:183], v[72:73], v[134:135] op_sel_hi:[0,1,1]
	v_pk_mul_f32 v[66:67], v[66:67], v[66:67]
	v_pk_mul_f32 v[64:65], v[64:65], v[64:65]
	v_pk_fma_f32 v[96:97], v[154:155], v[96:97], v[136:137] op_sel_hi:[0,1,1]
	v_pk_fma_f32 v[94:95], v[154:155], v[94:95], v[134:135] op_sel_hi:[0,1,1]
	v_pk_fma_f32 v[90:91], v[158:159], v[90:91], v[136:137] op_sel_hi:[0,1,1]
	v_pk_fma_f32 v[88:89], v[158:159], v[88:89], v[134:135] op_sel_hi:[0,1,1]
	v_pk_fma_f32 v[86:87], v[190:191], v[86:87], v[136:137] op_sel_hi:[0,1,1]
	v_pk_fma_f32 v[84:85], v[190:191], v[84:85], v[134:135] op_sel_hi:[0,1,1]
	v_pk_fma_f32 v[82:83], v[188:189], v[82:83], v[136:137] op_sel_hi:[0,1,1]
	v_pk_fma_f32 v[80:81], v[188:189], v[80:81], v[134:135] op_sel_hi:[0,1,1]
	v_pk_fma_f32 v[78:79], v[186:187], v[78:79], v[136:137] op_sel_hi:[0,1,1]
	v_pk_fma_f32 v[76:77], v[186:187], v[76:77], v[134:135] op_sel_hi:[0,1,1]
	v_max_f32_e32 v72, 0, v72
	v_max_f32_e32 v73, 0, v73
	v_max_f32_e32 v74, 0, v74
	v_max_f32_e32 v75, 0, v75
	v_cvt_pk_bf16_f32 v64, v64, v65
	v_cvt_pk_bf16_f32 v65, v66, v67
	v_max_f32_e32 v94, 0, v94
	v_max_f32_e32 v95, 0, v95
	v_max_f32_e32 v96, 0, v96
	v_max_f32_e32 v97, 0, v97
	v_max_f32_e32 v88, 0, v88
	v_max_f32_e32 v89, 0, v89
	v_max_f32_e32 v90, 0, v90
	v_max_f32_e32 v91, 0, v91
	v_max_f32_e32 v84, 0, v84
	v_max_f32_e32 v85, 0, v85
	v_max_f32_e32 v86, 0, v86
	v_max_f32_e32 v87, 0, v87
	v_max_f32_e32 v80, 0, v80
	v_max_f32_e32 v81, 0, v81
	v_max_f32_e32 v82, 0, v82
; __device__ __forceinline__ u32x2 pk4(f32x4 v) { u32x2 r; r.x = pk2(v.x, v.y); r.y = pk2(v.z, v.w); return r; }
;     __device__ __forceinline__ void operator()(int row, int col, f32x4 v, int, float&, float&) const { *(u32x2*)(O + (size_t)row * ldc + col) = pk4(v * s); }
;     __device__ __forceinline__ void operator()(const f32x4 (&acc)[2][2][4][2], const pg8::Unit& u, int wr, int wc, int fr, int fq) const {
;     ...
; #pragma unroll
;                 for (int ai = 0; ai < 2; ++ai)
; #pragma unroll
;                     for (int m = 0; m < 4; ++m) {
;                         f32x4 v = acc[ai][bj][m][n];
;                         if (fold) v = (v - c1v * mu[ai][m]) * rs[ai][m] + c2v;
;                         f(u.pm * 256 + ai * 128 + wr * 64 + m * 16 + fr, col, v, fq, ps1[ai][m], ps2[ai][m]);
;                     }
;     __device__ __forceinline__ void operator()(int row, int col, f32x4 v, int, float&, float&) const {
;         f32x4 r; r.x = fmaxf(v.x, 0.f); r.y = fmaxf(v.y, 0.f); r.z = fmaxf(v.z, 0.f); r.w = fmaxf(v.w, 0.f);
;         *(u32x2*)(O + (size_t)row * FF + col) = pk4(r * r);
;     }
	v_max_f32_e32 v83, 0, v83
	v_max_f32_e32 v76, 0, v76
	v_max_f32_e32 v77, 0, v77
	v_max_f32_e32 v78, 0, v78
	v_max_f32_e32 v79, 0, v79
	v_pk_mul_f32 v[74:75], v[74:75], v[74:75]
	v_pk_mul_f32 v[72:73], v[72:73], v[72:73]
	global_store_dwordx2 v[92:93], v[64:65], off offset:32
	v_add_u32_e32 v64, 0x80, v208
	v_pk_mul_f32 v[96:97], v[96:97], v[96:97]
	v_pk_mul_f32 v[94:95], v[94:95], v[94:95]
	v_pk_mul_f32 v[90:91], v[90:91], v[90:91]
	v_pk_mul_f32 v[88:89], v[88:89], v[88:89]
	v_pk_mul_f32 v[86:87], v[86:87], v[86:87]
	v_pk_mul_f32 v[84:85], v[84:85], v[84:85]
	v_pk_mul_f32 v[82:83], v[82:83], v[82:83]
	v_pk_mul_f32 v[80:81], v[80:81], v[80:81]
	v_pk_mul_f32 v[78:79], v[78:79], v[78:79]
	v_pk_mul_f32 v[76:77], v[76:77], v[76:77]
	v_cvt_pk_bf16_f32 v72, v72, v73
	v_cvt_pk_bf16_f32 v73, v74, v75
	v_ashrrev_i32_e32 v65, 31, v64
	v_cvt_pk_bf16_f32 v94, v94, v95
	v_cvt_pk_bf16_f32 v95, v96, v97
	v_cvt_pk_bf16_f32 v88, v88, v89
	v_cvt_pk_bf16_f32 v89, v90, v91
	v_cvt_pk_bf16_f32 v84, v84, v85
	v_cvt_pk_bf16_f32 v85, v86, v87
	v_cvt_pk_bf16_f32 v80, v80, v81
	v_cvt_pk_bf16_f32 v81, v82, v83
	v_cvt_pk_bf16_f32 v76, v76, v77
	v_cvt_pk_bf16_f32 v77, v78, v79
	global_store_dwordx2 v[100:101], v[72:73], off offset:32
	v_lshlrev_b64 v[72:73], 2, v[64:65]
	global_store_dwordx2 v[124:125], v[94:95], off offset:32
	global_store_dwordx2 v[120:121], v[88:89], off offset:32
	global_store_dwordx2 v[116:117], v[84:85], off offset:32
	global_store_dwordx2 v[112:113], v[80:81], off offset:32
	global_store_dwordx2 v[108:109], v[76:77], off offset:32
	v_lshl_add_u64 v[64:65], s[42:43], 0, v[72:73]
	ds_read_b128 v[64:67], v255 offset:128
	v_lshl_add_u64 v[72:73], s[46:47], 0, v[72:73]
	ds_read_b128 v[72:75], v255 offset:384
	s_waitcnt lgkmcnt(0)
	v_pk_fma_f32 v[28:29], v[160:161], v[64:65], v[28:29] op_sel_hi:[0,1,1] neg_lo:[1,0,0] neg_hi:[1,0,0]
	v_pk_fma_f32 v[30:31], v[160:161], v[66:67], v[30:31] op_sel_hi:[0,1,1] neg_lo:[1,0,0] neg_hi:[1,0,0]
	s_waitcnt lgkmcnt(0)
	v_pk_fma_f32 v[30:31], v[166:167], v[30:31], v[74:75] op_sel_hi:[0,1,1]
	v_pk_fma_f32 v[28:29], v[166:167], v[28:29], v[72:73] op_sel_hi:[0,1,1]
	v_pk_fma_f32 v[36:37], v[162:163], v[64:65], v[36:37] op_sel_hi:[0,1,1] neg_lo:[1,0,0] neg_hi:[1,0,0]
	v_pk_fma_f32 v[38:39], v[162:163], v[66:67], v[38:39] op_sel_hi:[0,1,1] neg_lo:[1,0,0] neg_hi:[1,0,0]
	v_max_f32_e32 v28, 0, v28
	v_max_f32_e32 v29, 0, v29
	v_max_f32_e32 v30, 0, v30
	v_max_f32_e32 v31, 0, v31
	v_pk_fma_f32 v[68:69], v[148:149], v[64:65], v[68:69] op_sel_hi:[0,1,1] neg_lo:[1,0,0] neg_hi:[1,0,0]
	v_pk_fma_f32 v[70:71], v[148:149], v[66:67], v[70:71] op_sel_hi:[0,1,1] neg_lo:[1,0,0] neg_hi:[1,0,0]
	v_pk_fma_f32 v[60:61], v[152:153], v[64:65], v[60:61] op_sel_hi:[0,1,1] neg_lo:[1,0,0] neg_hi:[1,0,0]
	v_pk_fma_f32 v[62:63], v[152:153], v[66:67], v[62:63] op_sel_hi:[0,1,1] neg_lo:[1,0,0] neg_hi:[1,0,0]
	v_pk_fma_f32 v[56:57], v[156:157], v[64:65], v[56:57] op_sel_hi:[0,1,1] neg_lo:[1,0,0] neg_hi:[1,0,0]
	v_pk_fma_f32 v[58:59], v[156:157], v[66:67], v[58:59] op_sel_hi:[0,1,1] neg_lo:[1,0,0] neg_hi:[1,0,0]
	v_pk_fma_f32 v[52:53], v[184:185], v[64:65], v[52:53] op_sel_hi:[0,1,1] neg_lo:[1,0,0] neg_hi:[1,0,0]
	v_pk_fma_f32 v[54:55], v[184:185], v[66:67], v[54:55] op_sel_hi:[0,1,1] neg_lo:[1,0,0] neg_hi:[1,0,0]
	v_pk_fma_f32 v[48:49], v[180:181], v[64:65], v[48:49] op_sel_hi:[0,1,1] neg_lo:[1,0,0] neg_hi:[1,0,0]
	v_pk_fma_f32 v[50:51], v[180:181], v[66:67], v[50:51] op_sel_hi:[0,1,1] neg_lo:[1,0,0] neg_hi:[1,0,0]
	v_pk_fma_f32 v[44:45], v[164:165], v[64:65], v[44:45] op_sel_hi:[0,1,1] neg_lo:[1,0,0] neg_hi:[1,0,0]
	v_pk_fma_f32 v[46:47], v[164:165], v[66:67], v[46:47] op_sel_hi:[0,1,1] neg_lo:[1,0,0] neg_hi:[1,0,0]
	v_pk_fma_f32 v[38:39], v[182:183], v[38:39], v[74:75] op_sel_hi:[0,1,1]
	v_pk_fma_f32 v[36:37], v[182:183], v[36:37], v[72:73] op_sel_hi:[0,1,1]
	v_pk_mul_f32 v[30:31], v[30:31], v[30:31]
	v_pk_mul_f32 v[28:29], v[28:29], v[28:29]
	v_pk_fma_f32 v[70:71], v[150:151], v[70:71], v[74:75] op_sel_hi:[0,1,1]
	v_pk_fma_f32 v[68:69], v[150:151], v[68:69], v[72:73] op_sel_hi:[0,1,1]
	v_pk_fma_f32 v[62:63], v[154:155], v[62:63], v[74:75] op_sel_hi:[0,1,1]
	v_pk_fma_f32 v[60:61], v[154:155], v[60:61], v[72:73] op_sel_hi:[0,1,1]
	v_pk_fma_f32 v[58:59], v[158:159], v[58:59], v[74:75] op_sel_hi:[0,1,1]
	v_pk_fma_f32 v[56:57], v[158:159], v[56:57], v[72:73] op_sel_hi:[0,1,1]
	v_pk_fma_f32 v[54:55], v[190:191], v[54:55], v[74:75] op_sel_hi:[0,1,1]
	v_pk_fma_f32 v[52:53], v[190:191], v[52:53], v[72:73] op_sel_hi:[0,1,1]
	v_pk_fma_f32 v[50:51], v[188:189], v[50:51], v[74:75] op_sel_hi:[0,1,1]
	v_pk_fma_f32 v[48:49], v[188:189], v[48:49], v[72:73] op_sel_hi:[0,1,1]
	v_pk_fma_f32 v[46:47], v[186:187], v[46:47], v[74:75] op_sel_hi:[0,1,1]
	v_pk_fma_f32 v[44:45], v[186:187], v[44:45], v[72:73] op_sel_hi:[0,1,1]
	v_max_f32_e32 v36, 0, v36
	v_max_f32_e32 v37, 0, v37
	v_max_f32_e32 v38, 0, v38
	v_max_f32_e32 v39, 0, v39
	v_cvt_pk_bf16_f32 v28, v28, v29
	v_cvt_pk_bf16_f32 v29, v30, v31
	v_max_f32_e32 v68, 0, v68
	v_max_f32_e32 v69, 0, v69
	v_max_f32_e32 v70, 0, v70
	v_max_f32_e32 v71, 0, v71
	v_max_f32_e32 v60, 0, v60
	v_max_f32_e32 v61, 0, v61
	v_max_f32_e32 v62, 0, v62
	v_max_f32_e32 v63, 0, v63
	v_max_f32_e32 v56, 0, v56
	v_max_f32_e32 v57, 0, v57
	v_max_f32_e32 v58, 0, v58
	v_max_f32_e32 v59, 0, v59
	v_max_f32_e32 v52, 0, v52
	v_max_f32_e32 v53, 0, v53
	v_max_f32_e32 v54, 0, v54
	v_max_f32_e32 v55, 0, v55
	v_max_f32_e32 v48, 0, v48
	v_max_f32_e32 v49, 0, v49
	v_max_f32_e32 v50, 0, v50
	v_max_f32_e32 v51, 0, v51
	v_max_f32_e32 v44, 0, v44
	v_max_f32_e32 v45, 0, v45
	v_max_f32_e32 v46, 0, v46
	v_max_f32_e32 v47, 0, v47
	v_pk_mul_f32 v[38:39], v[38:39], v[38:39]
; __device__ __forceinline__ u32x2 pk4(f32x4 v) { u32x2 r; r.x = pk2(v.x, v.y); r.y = pk2(v.z, v.w); return r; }
;     __device__ __forceinline__ void operator()(int row, int col, f32x4 v, int, float&, float&) const { *(u32x2*)(O + (size_t)row * ldc + col) = pk4(v * s); }
;     __device__ __forceinline__ void operator()(const f32x4 (&acc)[2][2][4][2], const pg8::Unit& u, int wr, int wc, int fr, int fq) const {
;     ...
; #pragma unroll
;                 for (int ai = 0; ai < 2; ++ai)
; #pragma unroll
;                     for (int m = 0; m < 4; ++m) {
;                         f32x4 v = acc[ai][bj][m][n];
;                         if (fold) v = (v - c1v * mu[ai][m]) * rs[ai][m] + c2v;
;                         f(u.pm * 256 + ai * 128 + wr * 64 + m * 16 + fr, col, v, fq, ps1[ai][m], ps2[ai][m]);
;                     }
;     __device__ __forceinline__ void operator()(int row, int col, f32x4 v, int, float&, float&) const {
;         f32x4 r; r.x = fmaxf(v.x, 0.f); r.y = fmaxf(v.y, 0.f); r.z = fmaxf(v.z, 0.f); r.w = fmaxf(v.w, 0.f);
;         *(u32x2*)(O + (size_t)row * FF + col) = pk4(r * r);
;     }
	v_pk_mul_f32 v[36:37], v[36:37], v[36:37]
	global_store_dwordx2 v[92:93], v[28:29], off offset:256
	v_add_u32_e32 v28, 0x90, v208
	v_pk_mul_f32 v[70:71], v[70:71], v[70:71]
	v_pk_mul_f32 v[68:69], v[68:69], v[68:69]
	v_pk_mul_f32 v[62:63], v[62:63], v[62:63]
	v_pk_mul_f32 v[60:61], v[60:61], v[60:61]
	v_pk_mul_f32 v[58:59], v[58:59], v[58:59]
	v_pk_mul_f32 v[56:57], v[56:57], v[56:57]
	v_pk_mul_f32 v[54:55], v[54:55], v[54:55]
	v_pk_mul_f32 v[52:53], v[52:53], v[52:53]
	v_pk_mul_f32 v[50:51], v[50:51], v[50:51]
	v_pk_mul_f32 v[48:49], v[48:49], v[48:49]
	v_pk_mul_f32 v[46:47], v[46:47], v[46:47]
	v_pk_mul_f32 v[44:45], v[44:45], v[44:45]
	v_cvt_pk_bf16_f32 v36, v36, v37
	v_cvt_pk_bf16_f32 v37, v38, v39
	v_ashrrev_i32_e32 v29, 31, v28
	v_cvt_pk_bf16_f32 v68, v68, v69
	v_cvt_pk_bf16_f32 v69, v70, v71
	v_cvt_pk_bf16_f32 v60, v60, v61
	v_cvt_pk_bf16_f32 v61, v62, v63
	v_cvt_pk_bf16_f32 v56, v56, v57
	v_cvt_pk_bf16_f32 v57, v58, v59
	v_cvt_pk_bf16_f32 v52, v52, v53
	v_cvt_pk_bf16_f32 v53, v54, v55
	v_cvt_pk_bf16_f32 v48, v48, v49
	v_cvt_pk_bf16_f32 v49, v50, v51
	v_cvt_pk_bf16_f32 v44, v44, v45
	v_cvt_pk_bf16_f32 v45, v46, v47
	global_store_dwordx2 v[100:101], v[36:37], off offset:256
	v_lshlrev_b64 v[36:37], 2, v[28:29]
	global_store_dwordx2 v[128:129], v[68:69], off offset:256
	global_store_dwordx2 v[124:125], v[60:61], off offset:256
	global_store_dwordx2 v[120:121], v[56:57], off offset:256
	global_store_dwordx2 v[116:117], v[52:53], off offset:256
	global_store_dwordx2 v[112:113], v[48:49], off offset:256
	global_store_dwordx2 v[108:109], v[44:45], off offset:256
	v_lshl_add_u64 v[28:29], s[42:43], 0, v[36:37]
	ds_read_b128 v[28:31], v255 offset:192
	v_lshl_add_u64 v[36:37], s[46:47], 0, v[36:37]
	ds_read_b128 v[36:39], v255 offset:448
	s_waitcnt lgkmcnt(0)
	v_pk_fma_f32 v[40:41], v[148:149], v[28:29], v[40:41] op_sel_hi:[0,1,1] neg_lo:[1,0,0] neg_hi:[1,0,0]
	v_pk_fma_f32 v[42:43], v[148:149], v[30:31], v[42:43] op_sel_hi:[0,1,1] neg_lo:[1,0,0] neg_hi:[1,0,0]
	v_pk_fma_f32 v[32:33], v[152:153], v[28:29], v[32:33] op_sel_hi:[0,1,1] neg_lo:[1,0,0] neg_hi:[1,0,0]
	v_pk_fma_f32 v[34:35], v[152:153], v[30:31], v[34:35] op_sel_hi:[0,1,1] neg_lo:[1,0,0] neg_hi:[1,0,0]
	v_pk_fma_f32 v[24:25], v[156:157], v[28:29], v[24:25] op_sel_hi:[0,1,1] neg_lo:[1,0,0] neg_hi:[1,0,0]
	v_pk_fma_f32 v[26:27], v[156:157], v[30:31], v[26:27] op_sel_hi:[0,1,1] neg_lo:[1,0,0] neg_hi:[1,0,0]
	v_pk_fma_f32 v[20:21], v[184:185], v[28:29], v[20:21] op_sel_hi:[0,1,1] neg_lo:[1,0,0] neg_hi:[1,0,0]
	v_pk_fma_f32 v[22:23], v[184:185], v[30:31], v[22:23] op_sel_hi:[0,1,1] neg_lo:[1,0,0] neg_hi:[1,0,0]
	v_pk_fma_f32 v[16:17], v[180:181], v[28:29], v[16:17] op_sel_hi:[0,1,1] neg_lo:[1,0,0] neg_hi:[1,0,0]
	v_pk_fma_f32 v[18:19], v[180:181], v[30:31], v[18:19] op_sel_hi:[0,1,1] neg_lo:[1,0,0] neg_hi:[1,0,0]
	v_pk_fma_f32 v[12:13], v[164:165], v[28:29], v[12:13] op_sel_hi:[0,1,1] neg_lo:[1,0,0] neg_hi:[1,0,0]
	v_pk_fma_f32 v[14:15], v[164:165], v[30:31], v[14:15] op_sel_hi:[0,1,1] neg_lo:[1,0,0] neg_hi:[1,0,0]
	v_pk_fma_f32 v[8:9], v[162:163], v[28:29], v[8:9] op_sel_hi:[0,1,1] neg_lo:[1,0,0] neg_hi:[1,0,0]
	v_pk_fma_f32 v[10:11], v[162:163], v[30:31], v[10:11] op_sel_hi:[0,1,1] neg_lo:[1,0,0] neg_hi:[1,0,0]
	v_pk_fma_f32 v[4:5], v[160:161], v[28:29], v[4:5] op_sel_hi:[0,1,1] neg_lo:[1,0,0] neg_hi:[1,0,0]
	v_pk_fma_f32 v[6:7], v[160:161], v[30:31], v[6:7] op_sel_hi:[0,1,1] neg_lo:[1,0,0] neg_hi:[1,0,0]
	s_waitcnt lgkmcnt(0)
; __device__ __forceinline__ u32x2 pk4(f32x4 v) { u32x2 r; r.x = pk2(v.x, v.y); r.y = pk2(v.z, v.w); return r; }
;     __device__ __forceinline__ void operator()(int row, int col, f32x4 v, int, float&, float&) const { *(u32x2*)(O + (size_t)row * ldc + col) = pk4(v * s); }
;     __device__ __forceinline__ void operator()(const f32x4 (&acc)[2][2][4][2], const pg8::Unit& u, int wr, int wc, int fr, int fq) const {
;     ...
; #pragma unroll
;                 for (int ai = 0; ai < 2; ++ai)
; #pragma unroll
;                     for (int m = 0; m < 4; ++m) {
;                         f32x4 v = acc[ai][bj][m][n];
;                         if (fold) v = (v - c1v * mu[ai][m]) * rs[ai][m] + c2v;
;                         f(u.pm * 256 + ai * 128 + wr * 64 + m * 16 + fr, col, v, fq, ps1[ai][m], ps2[ai][m]);
;                     }
;     __device__ __forceinline__ void operator()(int row, int col, f32x4 v, int, float&, float&) const {
;         f32x4 r; r.x = fmaxf(v.x, 0.f); r.y = fmaxf(v.y, 0.f); r.z = fmaxf(v.z, 0.f); r.w = fmaxf(v.w, 0.f);
;         *(u32x2*)(O + (size_t)row * FF + col) = pk4(r * r);
;     }
	v_pk_fma_f32 v[42:43], v[150:151], v[42:43], v[38:39] op_sel_hi:[0,1,1]
	v_pk_fma_f32 v[40:41], v[150:151], v[40:41], v[36:37] op_sel_hi:[0,1,1]
	v_pk_fma_f32 v[34:35], v[154:155], v[34:35], v[38:39] op_sel_hi:[0,1,1]
	v_pk_fma_f32 v[32:33], v[154:155], v[32:33], v[36:37] op_sel_hi:[0,1,1]
	v_pk_fma_f32 v[26:27], v[158:159], v[26:27], v[38:39] op_sel_hi:[0,1,1]
	v_pk_fma_f32 v[24:25], v[158:159], v[24:25], v[36:37] op_sel_hi:[0,1,1]
	v_pk_fma_f32 v[22:23], v[190:191], v[22:23], v[38:39] op_sel_hi:[0,1,1]
	v_pk_fma_f32 v[20:21], v[190:191], v[20:21], v[36:37] op_sel_hi:[0,1,1]
	v_pk_fma_f32 v[18:19], v[188:189], v[18:19], v[38:39] op_sel_hi:[0,1,1]
	v_pk_fma_f32 v[16:17], v[188:189], v[16:17], v[36:37] op_sel_hi:[0,1,1]
	v_pk_fma_f32 v[14:15], v[186:187], v[14:15], v[38:39] op_sel_hi:[0,1,1]
	v_pk_fma_f32 v[12:13], v[186:187], v[12:13], v[36:37] op_sel_hi:[0,1,1]
	v_pk_fma_f32 v[10:11], v[182:183], v[10:11], v[38:39] op_sel_hi:[0,1,1]
	v_pk_fma_f32 v[8:9], v[182:183], v[8:9], v[36:37] op_sel_hi:[0,1,1]
	v_pk_fma_f32 v[6:7], v[166:167], v[6:7], v[38:39] op_sel_hi:[0,1,1]
	v_pk_fma_f32 v[4:5], v[166:167], v[4:5], v[36:37] op_sel_hi:[0,1,1]
	v_max_f32_e32 v40, 0, v40
	v_max_f32_e32 v41, 0, v41
	v_max_f32_e32 v42, 0, v42
	v_max_f32_e32 v43, 0, v43
	v_max_f32_e32 v32, 0, v32
	v_max_f32_e32 v33, 0, v33
	v_max_f32_e32 v34, 0, v34
	v_max_f32_e32 v35, 0, v35
	v_max_f32_e32 v24, 0, v24
	v_max_f32_e32 v25, 0, v25
	v_max_f32_e32 v26, 0, v26
	v_max_f32_e32 v27, 0, v27
	v_max_f32_e32 v20, 0, v20
	v_max_f32_e32 v21, 0, v21
	v_max_f32_e32 v22, 0, v22
	v_max_f32_e32 v23, 0, v23
	v_max_f32_e32 v16, 0, v16
	v_max_f32_e32 v17, 0, v17
	v_max_f32_e32 v18, 0, v18
	v_max_f32_e32 v19, 0, v19
	v_max_f32_e32 v12, 0, v12
	v_max_f32_e32 v13, 0, v13
	v_max_f32_e32 v14, 0, v14
	v_max_f32_e32 v15, 0, v15
	v_max_f32_e32 v8, 0, v8
	v_max_f32_e32 v9, 0, v9
	v_max_f32_e32 v10, 0, v10
	v_max_f32_e32 v11, 0, v11
	v_max_f32_e32 v4, 0, v4
	v_max_f32_e32 v5, 0, v5
	v_max_f32_e32 v6, 0, v6
	v_max_f32_e32 v7, 0, v7
	v_pk_mul_f32 v[42:43], v[42:43], v[42:43]
	v_pk_mul_f32 v[40:41], v[40:41], v[40:41]
	v_pk_mul_f32 v[34:35], v[34:35], v[34:35]
	v_pk_mul_f32 v[32:33], v[32:33], v[32:33]
	v_pk_mul_f32 v[26:27], v[26:27], v[26:27]
	v_pk_mul_f32 v[24:25], v[24:25], v[24:25]
	v_pk_mul_f32 v[22:23], v[22:23], v[22:23]
	v_pk_mul_f32 v[20:21], v[20:21], v[20:21]
	v_pk_mul_f32 v[18:19], v[18:19], v[18:19]
	v_pk_mul_f32 v[16:17], v[16:17], v[16:17]
	v_pk_mul_f32 v[14:15], v[14:15], v[14:15]
	v_pk_mul_f32 v[12:13], v[12:13], v[12:13]
	v_pk_mul_f32 v[10:11], v[10:11], v[10:11]
	v_pk_mul_f32 v[8:9], v[8:9], v[8:9]
	v_pk_mul_f32 v[6:7], v[6:7], v[6:7]
	v_pk_mul_f32 v[4:5], v[4:5], v[4:5]
	v_cvt_pk_bf16_f32 v40, v40, v41
	v_cvt_pk_bf16_f32 v41, v42, v43
	v_cvt_pk_bf16_f32 v32, v32, v33
	v_cvt_pk_bf16_f32 v33, v34, v35
	v_cvt_pk_bf16_f32 v24, v24, v25
	v_cvt_pk_bf16_f32 v25, v26, v27
	v_cvt_pk_bf16_f32 v20, v20, v21
	v_cvt_pk_bf16_f32 v21, v22, v23
	v_cvt_pk_bf16_f32 v16, v16, v17
	v_cvt_pk_bf16_f32 v17, v18, v19
	v_cvt_pk_bf16_f32 v12, v12, v13
	v_cvt_pk_bf16_f32 v13, v14, v15
	v_cvt_pk_bf16_f32 v8, v8, v9
	v_cvt_pk_bf16_f32 v9, v10, v11
	v_cvt_pk_bf16_f32 v4, v4, v5
	v_cvt_pk_bf16_f32 v5, v6, v7
	global_store_dwordx2 v[128:129], v[40:41], off offset:288
	global_store_dwordx2 v[124:125], v[32:33], off offset:288
	global_store_dwordx2 v[120:121], v[24:25], off offset:288
	global_store_dwordx2 v[116:117], v[20:21], off offset:288
	global_store_dwordx2 v[112:113], v[16:17], off offset:288
	global_store_dwordx2 v[108:109], v[12:13], off offset:288
	global_store_dwordx2 v[100:101], v[8:9], off offset:288
	global_store_dwordx2 v[92:93], v[4:5], off offset:288
	s_cbranch_vccnz .LBB0_2288
	s_and_b64 vcc, exec, s[38:39]
	s_cbranch_vccnz .LBB0_2287
	s_barrier
	s_branch .LBB0_2287

; #define LAS __attribute__((address_space(3)))
; __global__ void __launch_bounds__(NWAVES * 64, 2) mega(Args args) {
;     extern __shared__ __attribute__((aligned(16))) unsigned char lds_raw[];
;     LAS unsigned char* lds = (LAS unsigned char*)lds_raw;
;     const int wave = __builtin_amdgcn_readfirstlane((int)threadIdx.x >> 6);
;     const int G = gridDim.x, bx = blockIdx.x;
;     const int gw_ = bx * NWAVES + wave, NGW = G * NWAVES;
	.amdhsa_kernel _Z4mega4Args
		.amdhsa_group_segment_fixed_size 0
		.amdhsa_private_segment_fixed_size 0
		.amdhsa_kernarg_size 472
		.amdhsa_user_sgpr_count 2
		.amdhsa_user_sgpr_dispatch_ptr 0
		.amdhsa_user_sgpr_queue_ptr 0
		.amdhsa_user_sgpr_kernarg_segment_ptr 1
		.amdhsa_user_sgpr_dispatch_id 0
		.amdhsa_user_sgpr_kernarg_preload_length 0
		.amdhsa_user_sgpr_kernarg_preload_offset 0
		.amdhsa_user_sgpr_private_segment_size 0
		.amdhsa_uses_dynamic_stack 0
		.amdhsa_enable_private_segment 0
		.amdhsa_system_sgpr_workgroup_id_x 1
		.amdhsa_system_sgpr_workgroup_id_y 0
		.amdhsa_system_sgpr_workgroup_id_z 0
		.amdhsa_system_sgpr_workgroup_info 0
		.amdhsa_system_vgpr_workitem_id 2
		.amdhsa_next_free_vgpr 256
		.amdhsa_next_free_sgpr 100
		.amdhsa_accum_offset 256
		.amdhsa_reserve_vcc 1
		.amdhsa_float_round_mode_32 0
		.amdhsa_float_round_mode_16_64 0
		.amdhsa_float_denorm_mode_32 3
		.amdhsa_float_denorm_mode_16_64 3
		.amdhsa_dx10_clamp 1
		.amdhsa_ieee_mode 1
		.amdhsa_fp16_overflow 0
		.amdhsa_tg_split 0
		.amdhsa_exception_fp_ieee_invalid_op 0
		.amdhsa_exception_fp_denorm_src 0
		.amdhsa_exception_fp_ieee_div_zero 0
		.amdhsa_exception_fp_ieee_overflow 0
		.amdhsa_exception_fp_ieee_underflow 0
		.amdhsa_exception_fp_ieee_inexact 0
		.amdhsa_exception_int_div_zero 0
	.end_amdhsa_kernel

; __global__ void __launch_bounds__(NWAVES * 64, 2) mega(Args args) {
amdhsa.kernels:
  - .agpr_count:     0
    .args:
      - .offset:         0
        .size:           216
        .value_kind:     by_value
      - .offset:         216
        .size:           4
        .value_kind:     hidden_block_count_x
      - .offset:         220
        .size:           4
        .value_kind:     hidden_block_count_y
      - .offset:         224
        .size:           4
        .value_kind:     hidden_block_count_z
      - .offset:         228
        .size:           2
        .value_kind:     hidden_group_size_x
      - .offset:         230
        .size:           2
        .value_kind:     hidden_group_size_y
      - .offset:         232
        .size:           2
        .value_kind:     hidden_group_size_z
      - .offset:         234
        .size:           2
        .value_kind:     hidden_remainder_x
      - .offset:         236
        .size:           2
        .value_kind:     hidden_remainder_y
      - .offset:         238
        .size:           2
        .value_kind:     hidden_remainder_z
      - .offset:         256
        .size:           8
        .value_kind:     hidden_global_offset_x
      - .offset:         264
        .size:           8
        .value_kind:     hidden_global_offset_y
      - .offset:         272
        .size:           8
        .value_kind:     hidden_global_offset_z
      - .offset:         280
        .size:           2
        .value_kind:     hidden_grid_dims
      - .offset:         304
        .size:           8
        .value_kind:     hidden_multigrid_sync_arg
      - .offset:         336
        .size:           4
        .value_kind:     hidden_dynamic_lds_size
    .group_segment_fixed_size: 0
    .kernarg_segment_align: 8
    .kernarg_segment_size: 472
    .language:       OpenCL C
    .language_version:
      - 2
      - 0
    .max_flat_workgroup_size: 512
    .name:           _Z4mega4Args
    .private_segment_fixed_size: 0
    .sgpr_count:     106
    .sgpr_spill_count: 319
    .symbol:         _Z4mega4Args.kd
    .uniform_work_group_size: 1
    .uses_dynamic_stack: false
    .vgpr_count:     256
    .vgpr_spill_count: 0
    .wavefront_size: 64
